# saddr-form DMA loads + staged fragment waits stacked on the M0-pad-free K-loops
# speedup vs baseline: 1.0004x; 1.0004x over previous
.Lkprio_5:
.LBB0_57:
	s_add_u32 s22, s0, 0xfffc0080
	s_addc_u32 s23, s1, -1
	s_add_i32 s65, 0, 0x10000
	v_add_u32_e32 v142, s65, v178
	ds_read_b128 v[130:133], v142
	ds_read_b128 v[134:137], v142 offset:1024
	ds_read_b128 v[138:141], v142 offset:2048
	ds_read_b128 v[142:145], v142 offset:3072
	s_cmp_eq_u32 s64, 12
	s_cselect_b32 s49, s37, s23
	s_cselect_b32 s48, s60, s22
	s_cselect_b32 s23, s35, s63
	s_cselect_b32 s22, s61, s62
	v_lshl_add_u64 v[186:187], s[0:1], 0, v[168:169]
	s_add_i32 m0, s47, 0xc000
	ds_read_b128 v[172:175], v180
	ds_read_b128 v[182:185], v180 offset:1024
	ds_read_b128 v[206:209], v180 offset:2048
	ds_read_b128 v[210:213], v180 offset:3072
	ds_read_b128 v[214:217], v180 offset:4096
	ds_read_b128 v[218:221], v180 offset:5120
	ds_read_b128 v[222:225], v180 offset:6144
	ds_read_b128 v[226:229], v180 offset:7168
	global_load_lds_dwordx4 v[186:187], off
	s_add_i32 m0, s47, 0xe000
	v_lshl_add_u64 v[186:187], s[0:1], 0, v[170:171]
	global_load_lds_dwordx4 v[186:187], off
	s_waitcnt lgkmcnt(8)
	s_barrier
	s_waitcnt lgkmcnt(7)
	v_mfma_f32_16x16x32_bf16 v[126:129], v[130:133], v[172:175], v[126:129]
	v_mfma_f32_16x16x32_bf16 v[122:125], v[138:141], v[172:175], v[122:125]
	s_waitcnt lgkmcnt(5)
	v_mfma_f32_16x16x32_bf16 v[114:117], v[130:133], v[206:209], v[114:117]
	v_mfma_f32_16x16x32_bf16 v[106:109], v[138:141], v[206:209], v[106:109]
	s_waitcnt lgkmcnt(3)
	v_mfma_f32_16x16x32_bf16 v[98:101], v[130:133], v[214:217], v[98:101]
	v_mfma_f32_16x16x32_bf16 v[90:93], v[138:141], v[214:217], v[90:93]
	s_waitcnt lgkmcnt(1)
	v_mfma_f32_16x16x32_bf16 v[82:85], v[130:133], v[222:225], v[82:85]
	v_mfma_f32_16x16x32_bf16 v[74:77], v[138:141], v[222:225], v[74:77]
	v_mfma_f32_16x16x32_bf16 v[126:129], v[134:137], v[182:185], v[126:129]
	v_mfma_f32_16x16x32_bf16 v[122:125], v[142:145], v[182:185], v[122:125]
	v_mfma_f32_16x16x32_bf16 v[114:117], v[134:137], v[210:213], v[114:117]
	v_mfma_f32_16x16x32_bf16 v[106:109], v[142:145], v[210:213], v[106:109]
	v_mfma_f32_16x16x32_bf16 v[98:101], v[134:137], v[218:221], v[98:101]
	v_mfma_f32_16x16x32_bf16 v[90:93], v[142:145], v[218:221], v[90:93]
	s_waitcnt lgkmcnt(0)
	v_mfma_f32_16x16x32_bf16 v[82:85], v[134:137], v[226:229], v[82:85]
	v_mfma_f32_16x16x32_bf16 v[74:77], v[142:145], v[226:229], v[74:77]
	s_barrier
	s_add_i32 s68, 0, 0x14000
	s_add_i32 s65, s65, s27
	v_add_u32_e32 v181, s68, v178
	v_lshl_add_u64 v[186:187], s[22:23], 0, v[0:1]
	s_mov_b32 m0, s65
	ds_read_b128 v[230:233], v181
	ds_read_b128 v[234:237], v181 offset:1024
	ds_read_b128 v[238:241], v181 offset:2048
	ds_read_b128 v[242:245], v181 offset:3072
	global_load_lds_dwordx4 v[186:187], off
	s_add_i32 m0, s65, 0x2000
	v_lshl_add_u64 v[246:247], s[22:23], 0, v[166:167]
	global_load_lds_dwordx4 v[246:247], off
	s_barrier
	s_waitcnt lgkmcnt(3)
	v_mfma_f32_16x16x32_bf16 v[118:121], v[230:233], v[172:175], v[118:121]
	s_waitcnt lgkmcnt(1)
	v_mfma_f32_16x16x32_bf16 v[110:113], v[238:241], v[172:175], v[110:113]
	v_mfma_f32_16x16x32_bf16 v[102:105], v[230:233], v[206:209], v[102:105]
	v_mfma_f32_16x16x32_bf16 v[94:97], v[238:241], v[206:209], v[94:97]
	v_mfma_f32_16x16x32_bf16 v[86:89], v[230:233], v[214:217], v[86:89]
	v_mfma_f32_16x16x32_bf16 v[78:81], v[238:241], v[214:217], v[78:81]
	v_mfma_f32_16x16x32_bf16 v[70:73], v[230:233], v[222:225], v[70:73]
	v_mfma_f32_16x16x32_bf16 v[66:69], v[238:241], v[222:225], v[66:69]
	v_mfma_f32_16x16x32_bf16 v[118:121], v[234:237], v[182:185], v[118:121]
	s_waitcnt lgkmcnt(0)
	v_mfma_f32_16x16x32_bf16 v[110:113], v[242:245], v[182:185], v[110:113]
	v_mfma_f32_16x16x32_bf16 v[102:105], v[234:237], v[210:213], v[102:105]
	v_mfma_f32_16x16x32_bf16 v[94:97], v[242:245], v[210:213], v[94:97]
	v_mfma_f32_16x16x32_bf16 v[86:89], v[234:237], v[218:221], v[86:89]
	v_mfma_f32_16x16x32_bf16 v[78:81], v[242:245], v[218:221], v[78:81]
	v_mfma_f32_16x16x32_bf16 v[70:73], v[234:237], v[226:229], v[70:73]
	v_mfma_f32_16x16x32_bf16 v[66:69], v[242:245], v[226:229], v[66:69]
	s_barrier
	s_mov_b32 m0, s47
	v_lshl_add_u64 v[248:249], s[48:49], 0, v[162:163]
	ds_read_b128 v[172:175], v180 offset:16384
	ds_read_b128 v[182:185], v180 offset:17408
	ds_read_b128 v[206:209], v180 offset:18432
	ds_read_b128 v[210:213], v180 offset:19456
	ds_read_b128 v[214:217], v180 offset:20480
	ds_read_b128 v[218:221], v180 offset:21504
	ds_read_b128 v[222:225], v180 offset:22528
	ds_read_b128 v[226:229], v180 offset:23552
	global_load_lds_dwordx4 v[248:249], off
	s_mov_b32 m0, s50
	v_lshl_add_u64 v[250:251], s[48:49], 0, v[164:165]
	global_load_lds_dwordx4 v[250:251], off
	s_barrier
	s_waitcnt lgkmcnt(7)
	v_mfma_f32_16x16x32_bf16 v[62:65], v[130:133], v[172:175], v[62:65]
	v_mfma_f32_16x16x32_bf16 v[58:61], v[138:141], v[172:175], v[58:61]
	s_waitcnt lgkmcnt(5)
	v_mfma_f32_16x16x32_bf16 v[50:53], v[130:133], v[206:209], v[50:53]
	v_mfma_f32_16x16x32_bf16 v[42:45], v[138:141], v[206:209], v[42:45]
	s_waitcnt lgkmcnt(3)
	v_mfma_f32_16x16x32_bf16 v[34:37], v[130:133], v[214:217], v[34:37]
	v_mfma_f32_16x16x32_bf16 v[26:29], v[138:141], v[214:217], v[26:29]
	s_waitcnt lgkmcnt(1)
	v_mfma_f32_16x16x32_bf16 v[18:21], v[130:133], v[222:225], v[18:21]
	v_mfma_f32_16x16x32_bf16 v[10:13], v[138:141], v[222:225], v[10:13]
	v_mfma_f32_16x16x32_bf16 v[62:65], v[134:137], v[182:185], v[62:65]
	v_mfma_f32_16x16x32_bf16 v[58:61], v[142:145], v[182:185], v[58:61]
	v_mfma_f32_16x16x32_bf16 v[50:53], v[134:137], v[210:213], v[50:53]
	v_mfma_f32_16x16x32_bf16 v[42:45], v[142:145], v[210:213], v[42:45]
	v_mfma_f32_16x16x32_bf16 v[34:37], v[134:137], v[218:221], v[34:37]
	v_mfma_f32_16x16x32_bf16 v[26:29], v[142:145], v[218:221], v[26:29]
	s_waitcnt lgkmcnt(0)
	v_mfma_f32_16x16x32_bf16 v[18:21], v[134:137], v[226:229], v[18:21]
	v_mfma_f32_16x16x32_bf16 v[10:13], v[142:145], v[226:229], v[10:13]
	s_barrier
	s_add_u32 s66, s22, 0x40000
	s_addc_u32 s67, s23, 0
	s_add_i32 s65, s68, s27
	s_mov_b32 m0, s65
	s_nop 0
	global_load_lds_dwordx4 v0, s[66:67]
	s_add_i32 m0, s65, 0x2000
	v_lshl_add_u64 v[130:131], s[66:67], 0, v[166:167]
	global_load_lds_dwordx4 v[130:131], off
	s_waitcnt vmcnt(6)
	s_barrier
	v_mfma_f32_16x16x32_bf16 v[54:57], v[230:233], v[172:175], v[54:57]
	v_mfma_f32_16x16x32_bf16 v[46:49], v[238:241], v[172:175], v[46:49]
	v_mfma_f32_16x16x32_bf16 v[38:41], v[230:233], v[206:209], v[38:41]
	v_mfma_f32_16x16x32_bf16 v[30:33], v[238:241], v[206:209], v[30:33]
	v_mfma_f32_16x16x32_bf16 v[22:25], v[230:233], v[214:217], v[22:25]
	v_mfma_f32_16x16x32_bf16 v[14:17], v[238:241], v[214:217], v[14:17]
	v_mfma_f32_16x16x32_bf16 v[6:9], v[230:233], v[222:225], v[6:9]
	v_mfma_f32_16x16x32_bf16 v[2:5], v[238:241], v[222:225], v[2:5]
	v_mfma_f32_16x16x32_bf16 v[54:57], v[234:237], v[182:185], v[54:57]
	v_mfma_f32_16x16x32_bf16 v[46:49], v[242:245], v[182:185], v[46:49]
	v_mfma_f32_16x16x32_bf16 v[38:41], v[234:237], v[210:213], v[38:41]
	v_mfma_f32_16x16x32_bf16 v[30:33], v[242:245], v[210:213], v[30:33]
	v_mfma_f32_16x16x32_bf16 v[22:25], v[234:237], v[218:221], v[22:25]
	v_mfma_f32_16x16x32_bf16 v[14:17], v[242:245], v[218:221], v[14:17]
	v_mfma_f32_16x16x32_bf16 v[6:9], v[234:237], v[226:229], v[6:9]
	v_mfma_f32_16x16x32_bf16 v[2:5], v[242:245], v[226:229], v[2:5]
	s_barrier
	s_add_i32 s65, 0, 0x18000
	v_add_u32_e32 v142, s65, v178
	ds_read_b128 v[130:133], v142
	ds_read_b128 v[134:137], v142 offset:1024
	ds_read_b128 v[138:141], v142 offset:2048
	ds_read_b128 v[142:145], v142 offset:3072
	s_add_u32 s48, s48, 0x40000
	s_addc_u32 s49, s49, 0
	s_mov_b32 m0, s51
	v_lshl_add_u64 v[230:231], s[48:49], 0, v[162:163]
	ds_read_b128 v[172:175], v180 offset:32768
	ds_read_b128 v[182:185], v180 offset:33792
	ds_read_b128 v[206:209], v180 offset:34816
	ds_read_b128 v[210:213], v180 offset:35840
	ds_read_b128 v[214:217], v180 offset:36864
	ds_read_b128 v[218:221], v180 offset:37888
	ds_read_b128 v[222:225], v180 offset:38912
	ds_read_b128 v[226:229], v180 offset:39936
	global_load_lds_dwordx4 v[230:231], off
	s_mov_b32 m0, s54
	v_lshl_add_u64 v[230:231], s[48:49], 0, v[164:165]
	global_load_lds_dwordx4 v[230:231], off
	s_waitcnt lgkmcnt(8)
	s_barrier
	s_waitcnt lgkmcnt(7)
	v_mfma_f32_16x16x32_bf16 v[126:129], v[130:133], v[172:175], v[126:129]
	v_mfma_f32_16x16x32_bf16 v[122:125], v[138:141], v[172:175], v[122:125]
	s_waitcnt lgkmcnt(5)
	v_mfma_f32_16x16x32_bf16 v[114:117], v[130:133], v[206:209], v[114:117]
	v_mfma_f32_16x16x32_bf16 v[106:109], v[138:141], v[206:209], v[106:109]
	s_waitcnt lgkmcnt(3)
	v_mfma_f32_16x16x32_bf16 v[98:101], v[130:133], v[214:217], v[98:101]
	v_mfma_f32_16x16x32_bf16 v[90:93], v[138:141], v[214:217], v[90:93]
	s_waitcnt lgkmcnt(1)
	v_mfma_f32_16x16x32_bf16 v[82:85], v[130:133], v[222:225], v[82:85]
	v_mfma_f32_16x16x32_bf16 v[74:77], v[138:141], v[222:225], v[74:77]
	v_mfma_f32_16x16x32_bf16 v[126:129], v[134:137], v[182:185], v[126:129]
	v_mfma_f32_16x16x32_bf16 v[122:125], v[142:145], v[182:185], v[122:125]
	v_mfma_f32_16x16x32_bf16 v[114:117], v[134:137], v[210:213], v[114:117]
	v_mfma_f32_16x16x32_bf16 v[106:109], v[142:145], v[210:213], v[106:109]
	v_mfma_f32_16x16x32_bf16 v[98:101], v[134:137], v[218:221], v[98:101]
	v_mfma_f32_16x16x32_bf16 v[90:93], v[142:145], v[218:221], v[90:93]
	s_waitcnt lgkmcnt(0)
	v_mfma_f32_16x16x32_bf16 v[82:85], v[134:137], v[226:229], v[82:85]
	v_mfma_f32_16x16x32_bf16 v[74:77], v[142:145], v[226:229], v[74:77]
	s_barrier
	s_add_i32 s48, 0, 0x1c000
	s_add_i32 s49, s65, s27
	v_add_u32_e32 v181, s48, v178
	v_lshl_add_u64 v[186:187], v[186:187], 0, s[94:95]
	s_mov_b32 m0, s49
	ds_read_b128 v[230:233], v181
	ds_read_b128 v[234:237], v181 offset:1024
	ds_read_b128 v[238:241], v181 offset:2048
	ds_read_b128 v[242:245], v181 offset:3072
	global_load_lds_dwordx4 v[186:187], off
	s_add_i32 m0, s49, 0x2000
	v_lshl_add_u64 v[186:187], v[246:247], 0, s[94:95]
	global_load_lds_dwordx4 v[186:187], off
	s_barrier
	s_waitcnt lgkmcnt(3)
	v_mfma_f32_16x16x32_bf16 v[118:121], v[230:233], v[172:175], v[118:121]
	s_waitcnt lgkmcnt(1)
	v_mfma_f32_16x16x32_bf16 v[110:113], v[238:241], v[172:175], v[110:113]
	v_mfma_f32_16x16x32_bf16 v[102:105], v[230:233], v[206:209], v[102:105]
	v_mfma_f32_16x16x32_bf16 v[94:97], v[238:241], v[206:209], v[94:97]
	v_mfma_f32_16x16x32_bf16 v[86:89], v[230:233], v[214:217], v[86:89]
	v_mfma_f32_16x16x32_bf16 v[78:81], v[238:241], v[214:217], v[78:81]
	v_mfma_f32_16x16x32_bf16 v[70:73], v[230:233], v[222:225], v[70:73]
	v_mfma_f32_16x16x32_bf16 v[66:69], v[238:241], v[222:225], v[66:69]
	v_mfma_f32_16x16x32_bf16 v[118:121], v[234:237], v[182:185], v[118:121]
	s_waitcnt lgkmcnt(0)
	v_mfma_f32_16x16x32_bf16 v[110:113], v[242:245], v[182:185], v[110:113]
	v_mfma_f32_16x16x32_bf16 v[102:105], v[234:237], v[210:213], v[102:105]
	v_mfma_f32_16x16x32_bf16 v[94:97], v[242:245], v[210:213], v[94:97]
	v_mfma_f32_16x16x32_bf16 v[86:89], v[234:237], v[218:221], v[86:89]
	v_mfma_f32_16x16x32_bf16 v[78:81], v[242:245], v[218:221], v[78:81]
	v_mfma_f32_16x16x32_bf16 v[70:73], v[234:237], v[226:229], v[70:73]
	v_mfma_f32_16x16x32_bf16 v[66:69], v[242:245], v[226:229], v[66:69]
	s_barrier
	s_mov_b32 m0, s55
	v_lshl_add_u64 v[186:187], v[248:249], 0, s[94:95]
	ds_read_b128 v[172:175], v180 offset:49152
	ds_read_b128 v[182:185], v180 offset:50176
	ds_read_b128 v[206:209], v180 offset:51200
	ds_read_b128 v[210:213], v180 offset:52224
	ds_read_b128 v[214:217], v180 offset:53248
	ds_read_b128 v[218:221], v180 offset:54272
	ds_read_b128 v[222:225], v180 offset:55296
	ds_read_b128 v[226:229], v180 offset:56320
	global_load_lds_dwordx4 v[186:187], off
	s_mov_b32 m0, s56
	v_lshl_add_u64 v[186:187], v[250:251], 0, s[94:95]
	global_load_lds_dwordx4 v[186:187], off
	s_barrier
	s_waitcnt lgkmcnt(7)
	v_mfma_f32_16x16x32_bf16 v[62:65], v[130:133], v[172:175], v[62:65]
	v_mfma_f32_16x16x32_bf16 v[58:61], v[138:141], v[172:175], v[58:61]
	s_waitcnt lgkmcnt(5)
	v_mfma_f32_16x16x32_bf16 v[50:53], v[130:133], v[206:209], v[50:53]
	v_mfma_f32_16x16x32_bf16 v[42:45], v[138:141], v[206:209], v[42:45]
	s_waitcnt lgkmcnt(3)
	v_mfma_f32_16x16x32_bf16 v[34:37], v[130:133], v[214:217], v[34:37]
	v_mfma_f32_16x16x32_bf16 v[26:29], v[138:141], v[214:217], v[26:29]
	s_waitcnt lgkmcnt(1)
	v_mfma_f32_16x16x32_bf16 v[18:21], v[130:133], v[222:225], v[18:21]
	v_mfma_f32_16x16x32_bf16 v[10:13], v[138:141], v[222:225], v[10:13]
	v_mfma_f32_16x16x32_bf16 v[62:65], v[134:137], v[182:185], v[62:65]
	v_mfma_f32_16x16x32_bf16 v[58:61], v[142:145], v[182:185], v[58:61]
	v_mfma_f32_16x16x32_bf16 v[50:53], v[134:137], v[210:213], v[50:53]
	v_mfma_f32_16x16x32_bf16 v[42:45], v[142:145], v[210:213], v[42:45]
	v_mfma_f32_16x16x32_bf16 v[34:37], v[134:137], v[218:221], v[34:37]
	v_mfma_f32_16x16x32_bf16 v[26:29], v[142:145], v[218:221], v[26:29]
	s_waitcnt lgkmcnt(0)
	v_mfma_f32_16x16x32_bf16 v[18:21], v[134:137], v[226:229], v[18:21]
	v_mfma_f32_16x16x32_bf16 v[10:13], v[142:145], v[226:229], v[10:13]
	s_barrier
	s_add_u32 s22, s22, 0x40080
	s_addc_u32 s23, s23, 0
	s_add_i32 s48, s48, s27
	s_mov_b32 m0, s48
	s_nop 0
	global_load_lds_dwordx4 v0, s[22:23]
	s_add_i32 m0, s48, 0x2000
	v_lshl_add_u64 v[130:131], s[22:23], 0, v[166:167]
	global_load_lds_dwordx4 v[130:131], off
	s_waitcnt vmcnt(6)
	s_barrier
	v_mfma_f32_16x16x32_bf16 v[54:57], v[230:233], v[172:175], v[54:57]
	v_mfma_f32_16x16x32_bf16 v[46:49], v[238:241], v[172:175], v[46:49]
	v_mfma_f32_16x16x32_bf16 v[38:41], v[230:233], v[206:209], v[38:41]
	v_mfma_f32_16x16x32_bf16 v[30:33], v[238:241], v[206:209], v[30:33]
	v_mfma_f32_16x16x32_bf16 v[22:25], v[230:233], v[214:217], v[22:25]
	v_mfma_f32_16x16x32_bf16 v[14:17], v[238:241], v[214:217], v[14:17]
	v_mfma_f32_16x16x32_bf16 v[6:9], v[230:233], v[222:225], v[6:9]
	v_mfma_f32_16x16x32_bf16 v[2:5], v[238:241], v[222:225], v[2:5]
	v_mfma_f32_16x16x32_bf16 v[54:57], v[234:237], v[182:185], v[54:57]
	v_mfma_f32_16x16x32_bf16 v[46:49], v[242:245], v[182:185], v[46:49]
	v_mfma_f32_16x16x32_bf16 v[38:41], v[234:237], v[210:213], v[38:41]
	v_mfma_f32_16x16x32_bf16 v[30:33], v[242:245], v[210:213], v[30:33]
	v_mfma_f32_16x16x32_bf16 v[22:25], v[234:237], v[218:221], v[22:25]
	v_mfma_f32_16x16x32_bf16 v[14:17], v[242:245], v[218:221], v[14:17]
	v_mfma_f32_16x16x32_bf16 v[6:9], v[234:237], v[226:229], v[6:9]
	v_mfma_f32_16x16x32_bf16 v[2:5], v[242:245], v[226:229], v[2:5]
	s_barrier
	s_add_i32 s64, s64, 2
	s_add_u32 s0, s0, 0x100
	s_addc_u32 s1, s1, 0
	s_add_u32 s62, s62, 0x100
	s_addc_u32 s63, s63, 0
	s_cmp_gt_u32 s64, 13
	s_cbranch_scc0 .LBB0_57
	v_lshl_or_b32 v172, s59, 8, v179
	v_ashrrev_i32_e32 v173, 31, v172
	v_cndmask_b32_e64 v131, 0, 1, s[2:3]
	v_lshl_add_u64 v[174:175], v[172:173], 2, s[8:9]
	v_mov_b32_e32 v130, 0
	v_cmp_ne_u32_e64 s[0:1], 1, v131
	s_andn2_b64 vcc, exec, s[2:3]
	v_mov_b32_e32 v134, 0
	v_mov_b32_e32 v135, 0
	v_mov_b32_e32 v136, 0
	v_mov_b32_e32 v137, 0
	s_cbranch_vccnz .LBB0_60
	global_load_dwordx4 v[134:137], v[174:175], off

.Lkprio_4:
.LBB0_95:
	s_add_u32 s22, s8, 0xfffc0080
	s_addc_u32 s23, s9, -1
	s_add_i32 s63, 0, 0x10000
	v_add_u32_e32 v78, s63, v178
	ds_read_b128 v[58:61], v78
	ds_read_b128 v[66:69], v78 offset:1024
	ds_read_b128 v[74:77], v78 offset:2048
	ds_read_b128 v[78:81], v78 offset:3072
	s_cmp_eq_u32 s49, 12
	s_cselect_b32 s29, s25, s23
	s_cselect_b32 s28, s26, s22
	s_cselect_b32 s23, s27, s47
	s_cselect_b32 s22, s30, s31
	v_lshl_add_u64 v[186:187], s[8:9], 0, v[168:169]
	s_add_i32 m0, s3, 0xc000
	ds_read_b128 v[172:175], v180
	ds_read_b128 v[182:185], v180 offset:1024
	ds_read_b128 v[206:209], v180 offset:2048
	ds_read_b128 v[210:213], v180 offset:3072
	ds_read_b128 v[214:217], v180 offset:4096
	ds_read_b128 v[218:221], v180 offset:5120
	ds_read_b128 v[222:225], v180 offset:6144
	ds_read_b128 v[226:229], v180 offset:7168
	global_load_lds_dwordx4 v[186:187], off
	s_add_i32 m0, s3, 0xe000
	s_nop 0
	global_load_lds_dwordx4 v170, s[8:9]
	s_waitcnt lgkmcnt(8)
	s_barrier
	s_waitcnt lgkmcnt(7)
	v_mfma_f32_16x16x32_bf16 v[142:145], v[58:61], v[172:175], v[142:145]
	v_mfma_f32_16x16x32_bf16 v[138:141], v[74:77], v[172:175], v[138:141]
	s_waitcnt lgkmcnt(5)
	v_mfma_f32_16x16x32_bf16 v[126:129], v[58:61], v[206:209], v[126:129]
	v_mfma_f32_16x16x32_bf16 v[118:121], v[74:77], v[206:209], v[118:121]
	s_waitcnt lgkmcnt(3)
	v_mfma_f32_16x16x32_bf16 v[110:113], v[58:61], v[214:217], v[110:113]
	v_mfma_f32_16x16x32_bf16 v[102:105], v[74:77], v[214:217], v[102:105]
	s_waitcnt lgkmcnt(1)
	v_mfma_f32_16x16x32_bf16 v[94:97], v[58:61], v[222:225], v[94:97]
	v_mfma_f32_16x16x32_bf16 v[86:89], v[74:77], v[222:225], v[86:89]
	v_mfma_f32_16x16x32_bf16 v[142:145], v[66:69], v[182:185], v[142:145]
	v_mfma_f32_16x16x32_bf16 v[138:141], v[78:81], v[182:185], v[138:141]
	v_mfma_f32_16x16x32_bf16 v[126:129], v[66:69], v[210:213], v[126:129]
	v_mfma_f32_16x16x32_bf16 v[118:121], v[78:81], v[210:213], v[118:121]
	v_mfma_f32_16x16x32_bf16 v[110:113], v[66:69], v[218:221], v[110:113]
	v_mfma_f32_16x16x32_bf16 v[102:105], v[78:81], v[218:221], v[102:105]
	s_waitcnt lgkmcnt(0)
	v_mfma_f32_16x16x32_bf16 v[94:97], v[66:69], v[226:229], v[94:97]
	v_mfma_f32_16x16x32_bf16 v[86:89], v[78:81], v[226:229], v[86:89]
	s_barrier
	s_add_i32 s66, 0, 0x14000
	s_add_i32 s63, s63, s37
	v_add_u32_e32 v181, s66, v178
	v_lshl_add_u64 v[186:187], s[22:23], 0, v[0:1]
	s_mov_b32 m0, s63
	ds_read_b128 v[230:233], v181
	ds_read_b128 v[234:237], v181 offset:1024
	ds_read_b128 v[238:241], v181 offset:2048
	ds_read_b128 v[242:245], v181 offset:3072
	global_load_lds_dwordx4 v[186:187], off
	s_add_i32 m0, s63, 0x2000
	v_lshl_add_u64 v[246:247], s[22:23], 0, v[166:167]
	global_load_lds_dwordx4 v[246:247], off
	s_barrier
	s_waitcnt lgkmcnt(3)
	v_mfma_f32_16x16x32_bf16 v[134:137], v[230:233], v[172:175], v[134:137]
	s_waitcnt lgkmcnt(1)
	v_mfma_f32_16x16x32_bf16 v[130:133], v[238:241], v[172:175], v[130:133]
	v_mfma_f32_16x16x32_bf16 v[122:125], v[230:233], v[206:209], v[122:125]
	v_mfma_f32_16x16x32_bf16 v[114:117], v[238:241], v[206:209], v[114:117]
	v_mfma_f32_16x16x32_bf16 v[106:109], v[230:233], v[214:217], v[106:109]
	v_mfma_f32_16x16x32_bf16 v[98:101], v[238:241], v[214:217], v[98:101]
	v_mfma_f32_16x16x32_bf16 v[90:93], v[230:233], v[222:225], v[90:93]
	v_mfma_f32_16x16x32_bf16 v[82:85], v[238:241], v[222:225], v[82:85]
	v_mfma_f32_16x16x32_bf16 v[134:137], v[234:237], v[182:185], v[134:137]
	s_waitcnt lgkmcnt(0)
	v_mfma_f32_16x16x32_bf16 v[130:133], v[242:245], v[182:185], v[130:133]
	v_mfma_f32_16x16x32_bf16 v[122:125], v[234:237], v[210:213], v[122:125]
	v_mfma_f32_16x16x32_bf16 v[114:117], v[242:245], v[210:213], v[114:117]
	v_mfma_f32_16x16x32_bf16 v[106:109], v[234:237], v[218:221], v[106:109]
	v_mfma_f32_16x16x32_bf16 v[98:101], v[242:245], v[218:221], v[98:101]
	v_mfma_f32_16x16x32_bf16 v[90:93], v[234:237], v[226:229], v[90:93]
	v_mfma_f32_16x16x32_bf16 v[82:85], v[242:245], v[226:229], v[82:85]
	s_barrier
	s_mov_b32 m0, s3
	v_lshl_add_u64 v[248:249], s[28:29], 0, v[162:163]
	ds_read_b128 v[172:175], v180 offset:16384
	ds_read_b128 v[182:185], v180 offset:17408
	ds_read_b128 v[206:209], v180 offset:18432
	ds_read_b128 v[210:213], v180 offset:19456
	ds_read_b128 v[214:217], v180 offset:20480
	ds_read_b128 v[218:221], v180 offset:21504
	ds_read_b128 v[222:225], v180 offset:22528
	ds_read_b128 v[226:229], v180 offset:23552
	global_load_lds_dwordx4 v[248:249], off
	s_mov_b32 m0, s56
	v_lshl_add_u64 v[250:251], s[28:29], 0, v[164:165]
	global_load_lds_dwordx4 v[250:251], off
	s_barrier
	s_waitcnt lgkmcnt(7)
	v_mfma_f32_16x16x32_bf16 v[70:73], v[58:61], v[172:175], v[70:73]
	v_mfma_f32_16x16x32_bf16 v[54:57], v[74:77], v[172:175], v[54:57]
	s_waitcnt lgkmcnt(5)
	v_mfma_f32_16x16x32_bf16 v[46:49], v[58:61], v[206:209], v[46:49]
	v_mfma_f32_16x16x32_bf16 v[38:41], v[74:77], v[206:209], v[38:41]
	s_waitcnt lgkmcnt(3)
	v_mfma_f32_16x16x32_bf16 v[30:33], v[58:61], v[214:217], v[30:33]
	v_mfma_f32_16x16x32_bf16 v[22:25], v[74:77], v[214:217], v[22:25]
	s_waitcnt lgkmcnt(1)
	v_mfma_f32_16x16x32_bf16 v[14:17], v[58:61], v[222:225], v[14:17]
	v_mfma_f32_16x16x32_bf16 v[6:9], v[74:77], v[222:225], v[6:9]
	v_mfma_f32_16x16x32_bf16 v[70:73], v[66:69], v[182:185], v[70:73]
	v_mfma_f32_16x16x32_bf16 v[54:57], v[78:81], v[182:185], v[54:57]
	v_mfma_f32_16x16x32_bf16 v[46:49], v[66:69], v[210:213], v[46:49]
	v_mfma_f32_16x16x32_bf16 v[38:41], v[78:81], v[210:213], v[38:41]
	v_mfma_f32_16x16x32_bf16 v[30:33], v[66:69], v[218:221], v[30:33]
	v_mfma_f32_16x16x32_bf16 v[22:25], v[78:81], v[218:221], v[22:25]
	s_waitcnt lgkmcnt(0)
	v_mfma_f32_16x16x32_bf16 v[14:17], v[66:69], v[226:229], v[14:17]
	v_mfma_f32_16x16x32_bf16 v[6:9], v[78:81], v[226:229], v[6:9]
	s_barrier
	s_add_u32 s64, s22, 0x40000
	s_addc_u32 s65, s23, 0
	s_add_i32 s63, s66, s37
	s_mov_b32 m0, s63
	s_nop 0
	global_load_lds_dwordx4 v0, s[64:65]
	s_add_i32 m0, s63, 0x2000
	s_nop 0
	global_load_lds_dwordx4 v166, s[64:65]
	s_waitcnt vmcnt(6)
	s_barrier
	v_mfma_f32_16x16x32_bf16 v[50:53], v[238:241], v[172:175], v[50:53]
	v_mfma_f32_16x16x32_bf16 v[42:45], v[230:233], v[206:209], v[42:45]
	v_mfma_f32_16x16x32_bf16 v[34:37], v[238:241], v[206:209], v[34:37]
	v_mfma_f32_16x16x32_bf16 v[26:29], v[230:233], v[214:217], v[26:29]
	v_mfma_f32_16x16x32_bf16 v[18:21], v[238:241], v[214:217], v[18:21]
	v_mfma_f32_16x16x32_bf16 v[10:13], v[230:233], v[222:225], v[10:13]
	v_mfma_f32_16x16x32_bf16 v[2:5], v[238:241], v[222:225], v[2:5]
	v_mfma_f32_16x16x32_bf16 v[58:61], v[230:233], v[172:175], v[62:65]
	v_mfma_f32_16x16x32_bf16 v[50:53], v[242:245], v[182:185], v[50:53]
	v_mfma_f32_16x16x32_bf16 v[42:45], v[234:237], v[210:213], v[42:45]
	v_mfma_f32_16x16x32_bf16 v[34:37], v[242:245], v[210:213], v[34:37]
	v_mfma_f32_16x16x32_bf16 v[26:29], v[234:237], v[218:221], v[26:29]
	v_mfma_f32_16x16x32_bf16 v[18:21], v[242:245], v[218:221], v[18:21]
	v_mfma_f32_16x16x32_bf16 v[10:13], v[234:237], v[226:229], v[10:13]
	v_mfma_f32_16x16x32_bf16 v[2:5], v[242:245], v[226:229], v[2:5]
	v_mfma_f32_16x16x32_bf16 v[58:61], v[234:237], v[182:185], v[58:61]
	s_barrier
	s_add_i32 s63, 0, 0x18000
	v_add_u32_e32 v78, s63, v178
	ds_read_b128 v[62:65], v78
	ds_read_b128 v[66:69], v78 offset:1024
	ds_read_b128 v[74:77], v78 offset:2048
	ds_read_b128 v[78:81], v78 offset:3072
	s_add_u32 s28, s28, 0x40000
	s_addc_u32 s29, s29, 0
	s_mov_b32 m0, s57
	v_lshl_add_u64 v[230:231], s[28:29], 0, v[162:163]
	ds_read_b128 v[172:175], v180 offset:32768
	ds_read_b128 v[182:185], v180 offset:33792
	ds_read_b128 v[206:209], v180 offset:34816
	ds_read_b128 v[210:213], v180 offset:35840
	ds_read_b128 v[214:217], v180 offset:36864
	ds_read_b128 v[218:221], v180 offset:37888
	ds_read_b128 v[222:225], v180 offset:38912
	ds_read_b128 v[226:229], v180 offset:39936
	global_load_lds_dwordx4 v[230:231], off
	s_mov_b32 m0, s58
	s_nop 0
	global_load_lds_dwordx4 v164, s[28:29]
	s_waitcnt lgkmcnt(8)
	s_barrier
	s_waitcnt lgkmcnt(7)
	v_mfma_f32_16x16x32_bf16 v[142:145], v[62:65], v[172:175], v[142:145]
	v_mfma_f32_16x16x32_bf16 v[138:141], v[74:77], v[172:175], v[138:141]
	s_waitcnt lgkmcnt(5)
	v_mfma_f32_16x16x32_bf16 v[126:129], v[62:65], v[206:209], v[126:129]
	v_mfma_f32_16x16x32_bf16 v[118:121], v[74:77], v[206:209], v[118:121]
	s_waitcnt lgkmcnt(3)
	v_mfma_f32_16x16x32_bf16 v[110:113], v[62:65], v[214:217], v[110:113]
	v_mfma_f32_16x16x32_bf16 v[102:105], v[74:77], v[214:217], v[102:105]
	s_waitcnt lgkmcnt(1)
	v_mfma_f32_16x16x32_bf16 v[94:97], v[62:65], v[222:225], v[94:97]
	v_mfma_f32_16x16x32_bf16 v[86:89], v[74:77], v[222:225], v[86:89]
	v_mfma_f32_16x16x32_bf16 v[142:145], v[66:69], v[182:185], v[142:145]
	v_mfma_f32_16x16x32_bf16 v[138:141], v[78:81], v[182:185], v[138:141]
	v_mfma_f32_16x16x32_bf16 v[126:129], v[66:69], v[210:213], v[126:129]
	v_mfma_f32_16x16x32_bf16 v[118:121], v[78:81], v[210:213], v[118:121]
	v_mfma_f32_16x16x32_bf16 v[110:113], v[66:69], v[218:221], v[110:113]
	v_mfma_f32_16x16x32_bf16 v[102:105], v[78:81], v[218:221], v[102:105]
	s_waitcnt lgkmcnt(0)
	v_mfma_f32_16x16x32_bf16 v[94:97], v[66:69], v[226:229], v[94:97]
	v_mfma_f32_16x16x32_bf16 v[86:89], v[78:81], v[226:229], v[86:89]
	s_barrier
	s_add_i32 s28, 0, 0x1c000
	s_add_i32 s29, s63, s37
	v_add_u32_e32 v181, s28, v178
	v_lshl_add_u64 v[186:187], v[186:187], 0, s[94:95]
	s_mov_b32 m0, s29
	ds_read_b128 v[230:233], v181
	ds_read_b128 v[234:237], v181 offset:1024
	ds_read_b128 v[238:241], v181 offset:2048
	ds_read_b128 v[242:245], v181 offset:3072
	global_load_lds_dwordx4 v[186:187], off
	s_add_i32 m0, s29, 0x2000
	v_lshl_add_u64 v[186:187], v[246:247], 0, s[94:95]
	global_load_lds_dwordx4 v[186:187], off
	s_barrier
	s_waitcnt lgkmcnt(3)
	v_mfma_f32_16x16x32_bf16 v[134:137], v[230:233], v[172:175], v[134:137]
	s_waitcnt lgkmcnt(1)
	v_mfma_f32_16x16x32_bf16 v[130:133], v[238:241], v[172:175], v[130:133]
	v_mfma_f32_16x16x32_bf16 v[122:125], v[230:233], v[206:209], v[122:125]
	v_mfma_f32_16x16x32_bf16 v[114:117], v[238:241], v[206:209], v[114:117]
	v_mfma_f32_16x16x32_bf16 v[106:109], v[230:233], v[214:217], v[106:109]
	v_mfma_f32_16x16x32_bf16 v[98:101], v[238:241], v[214:217], v[98:101]
	v_mfma_f32_16x16x32_bf16 v[90:93], v[230:233], v[222:225], v[90:93]
	v_mfma_f32_16x16x32_bf16 v[82:85], v[238:241], v[222:225], v[82:85]
	v_mfma_f32_16x16x32_bf16 v[134:137], v[234:237], v[182:185], v[134:137]
	s_waitcnt lgkmcnt(0)
	v_mfma_f32_16x16x32_bf16 v[130:133], v[242:245], v[182:185], v[130:133]
	v_mfma_f32_16x16x32_bf16 v[122:125], v[234:237], v[210:213], v[122:125]
	v_mfma_f32_16x16x32_bf16 v[114:117], v[242:245], v[210:213], v[114:117]
	v_mfma_f32_16x16x32_bf16 v[106:109], v[234:237], v[218:221], v[106:109]
	v_mfma_f32_16x16x32_bf16 v[98:101], v[242:245], v[218:221], v[98:101]
	v_mfma_f32_16x16x32_bf16 v[90:93], v[234:237], v[226:229], v[90:93]
	v_mfma_f32_16x16x32_bf16 v[82:85], v[242:245], v[226:229], v[82:85]
	s_barrier
	s_mov_b32 m0, s59
	v_lshl_add_u64 v[186:187], v[248:249], 0, s[94:95]
	ds_read_b128 v[172:175], v180 offset:49152
	ds_read_b128 v[182:185], v180 offset:50176
	ds_read_b128 v[206:209], v180 offset:51200
	ds_read_b128 v[210:213], v180 offset:52224
	ds_read_b128 v[214:217], v180 offset:53248
	ds_read_b128 v[218:221], v180 offset:54272
	ds_read_b128 v[222:225], v180 offset:55296
	ds_read_b128 v[226:229], v180 offset:56320
	global_load_lds_dwordx4 v[186:187], off
	s_mov_b32 m0, s60
	v_lshl_add_u64 v[186:187], v[250:251], 0, s[94:95]
	global_load_lds_dwordx4 v[186:187], off
	s_barrier
	s_waitcnt lgkmcnt(7)
	v_mfma_f32_16x16x32_bf16 v[70:73], v[62:65], v[172:175], v[70:73]
	v_mfma_f32_16x16x32_bf16 v[54:57], v[74:77], v[172:175], v[54:57]
	s_waitcnt lgkmcnt(5)
	v_mfma_f32_16x16x32_bf16 v[46:49], v[62:65], v[206:209], v[46:49]
	v_mfma_f32_16x16x32_bf16 v[38:41], v[74:77], v[206:209], v[38:41]
	s_waitcnt lgkmcnt(3)
	v_mfma_f32_16x16x32_bf16 v[30:33], v[62:65], v[214:217], v[30:33]
	v_mfma_f32_16x16x32_bf16 v[22:25], v[74:77], v[214:217], v[22:25]
	s_waitcnt lgkmcnt(1)
	v_mfma_f32_16x16x32_bf16 v[14:17], v[62:65], v[222:225], v[14:17]
	v_mfma_f32_16x16x32_bf16 v[6:9], v[74:77], v[222:225], v[6:9]
	v_mfma_f32_16x16x32_bf16 v[70:73], v[66:69], v[182:185], v[70:73]
	v_mfma_f32_16x16x32_bf16 v[54:57], v[78:81], v[182:185], v[54:57]
	v_mfma_f32_16x16x32_bf16 v[46:49], v[66:69], v[210:213], v[46:49]
	v_mfma_f32_16x16x32_bf16 v[38:41], v[78:81], v[210:213], v[38:41]
	v_mfma_f32_16x16x32_bf16 v[30:33], v[66:69], v[218:221], v[30:33]
	v_mfma_f32_16x16x32_bf16 v[22:25], v[78:81], v[218:221], v[22:25]
	s_waitcnt lgkmcnt(0)
	v_mfma_f32_16x16x32_bf16 v[14:17], v[66:69], v[226:229], v[14:17]
	v_mfma_f32_16x16x32_bf16 v[6:9], v[78:81], v[226:229], v[6:9]
	s_barrier
	s_add_u32 s22, s22, 0x40080
	s_addc_u32 s23, s23, 0
	s_add_i32 s28, s28, s37
	s_mov_b32 m0, s28
	s_nop 0
	global_load_lds_dwordx4 v0, s[22:23]
	s_add_i32 m0, s28, 0x2000
	s_nop 0
	global_load_lds_dwordx4 v166, s[22:23]
	s_waitcnt vmcnt(6)
	s_barrier
	v_mfma_f32_16x16x32_bf16 v[58:61], v[230:233], v[172:175], v[58:61]
	v_mfma_f32_16x16x32_bf16 v[50:53], v[238:241], v[172:175], v[50:53]
	v_mfma_f32_16x16x32_bf16 v[42:45], v[230:233], v[206:209], v[42:45]
	v_mfma_f32_16x16x32_bf16 v[34:37], v[238:241], v[206:209], v[34:37]
	v_mfma_f32_16x16x32_bf16 v[26:29], v[230:233], v[214:217], v[26:29]
	v_mfma_f32_16x16x32_bf16 v[18:21], v[238:241], v[214:217], v[18:21]
	v_mfma_f32_16x16x32_bf16 v[10:13], v[230:233], v[222:225], v[10:13]
	v_mfma_f32_16x16x32_bf16 v[2:5], v[238:241], v[222:225], v[2:5]
	v_mfma_f32_16x16x32_bf16 v[62:65], v[234:237], v[182:185], v[58:61]
	v_mfma_f32_16x16x32_bf16 v[50:53], v[242:245], v[182:185], v[50:53]
	v_mfma_f32_16x16x32_bf16 v[42:45], v[234:237], v[210:213], v[42:45]
	v_mfma_f32_16x16x32_bf16 v[34:37], v[242:245], v[210:213], v[34:37]
	v_mfma_f32_16x16x32_bf16 v[26:29], v[234:237], v[218:221], v[26:29]
	v_mfma_f32_16x16x32_bf16 v[18:21], v[242:245], v[218:221], v[18:21]
	v_mfma_f32_16x16x32_bf16 v[10:13], v[234:237], v[226:229], v[10:13]
	v_mfma_f32_16x16x32_bf16 v[2:5], v[242:245], v[226:229], v[2:5]
	s_barrier
	s_add_i32 s49, s49, 2
	s_add_u32 s8, s8, 0x100
	s_addc_u32 s9, s9, 0
	s_add_u32 s31, s31, 0x100
	s_addc_u32 s47, s47, 0
	s_cmp_gt_u32 s49, 13
	s_cbranch_scc0 .LBB0_95
	v_lshl_or_b32 v172, s24, 7, v179
	v_ashrrev_i32_e32 v173, 31, v172
	v_lshlrev_b64 v[58:59], 2, v[172:173]
	v_lshl_add_u64 v[60:61], s[40:41], 0, v[58:59]
	v_lshl_add_u64 v[74:75], s[44:45], 0, v[58:59]
	global_load_dwordx4 v[66:69], v[60:61], off offset:16
	global_load_dwordx4 v[78:81], v[60:61], off
	s_nop 0
	global_load_dwordx4 v[58:61], v[74:75], off offset:16
	s_nop 0
	global_load_dwordx4 v[74:77], v[74:75], off
	v_lshl_add_u32 v174, s2, 8, v177
	v_ashrrev_i32_e32 v175, 31, v174
	v_lshl_add_u64 v[172:173], v[172:173], 1, s[20:21]
	v_lshlrev_b64 v[182:183], 11, v[174:175]
	s_mov_b32 s2, 0x50000
	s_mov_b32 s24, s46
	s_mov_b64 s[22:23], s[54:55]
	s_mov_b64 s[8:9], s[50:51]
	s_waitcnt vmcnt(0)
	v_add_f32_e32 v138, v138, v66
	v_add_f32_e32 v126, v126, v78
	v_add_f32_e32 v130, v130, v58
	v_mul_f32_e32 v130, 0xbfb8aa3b, v130
	v_add_f32_e32 v131, v131, v59
	v_add_f32_e32 v122, v122, v74
	v_exp_f32_e32 v130, v130
	v_mul_f32_e32 v131, 0xbfb8aa3b, v131
	v_mul_f32_e32 v122, 0xbfb8aa3b, v122
	v_add_f32_e32 v123, v123, v75
	v_exp_f32_e32 v131, v131
	v_exp_f32_e32 v122, v122
	v_mul_f32_e32 v123, 0xbfb8aa3b, v123
	v_add_f32_e32 v124, v124, v76
	v_exp_f32_e32 v123, v123
	v_mul_f32_e32 v124, 0xbfb8aa3b, v124
	v_add_f32_e32 v125, v125, v77
	v_add_f32_e32 v114, v114, v58
	v_exp_f32_e32 v124, v124
	v_mul_f32_e32 v125, 0xbfb8aa3b, v125
	v_mul_f32_e32 v114, 0xbfb8aa3b, v114
	v_add_f32_e32 v115, v115, v59
	v_add_f32_e32 v106, v106, v74
	v_add_f32_e32 v130, 1.0, v130
	v_exp_f32_e32 v125, v125
	v_exp_f32_e32 v114, v114
	v_mul_f32_e32 v115, 0xbfb8aa3b, v115
	v_mul_f32_e32 v106, 0xbfb8aa3b, v106
	v_add_f32_e32 v107, v107, v75
	v_rcp_f32_e32 v130, v130
	v_add_f32_e32 v131, 1.0, v131
	v_add_f32_e32 v122, 1.0, v122
	v_exp_f32_e32 v115, v115
	v_exp_f32_e32 v106, v106
	v_mul_f32_e32 v107, 0xbfb8aa3b, v107
	v_add_f32_e32 v108, v108, v76
	v_rcp_f32_e32 v131, v131
	v_rcp_f32_e32 v122, v122
	v_add_f32_e32 v123, 1.0, v123
	v_exp_f32_e32 v107, v107
	v_mul_f32_e32 v108, 0xbfb8aa3b, v108
	v_add_f32_e32 v109, v109, v77
	v_add_f32_e32 v98, v98, v58
	v_rcp_f32_e32 v123, v123
	v_add_f32_e32 v124, 1.0, v124
	v_exp_f32_e32 v108, v108
	v_mul_f32_e32 v109, 0xbfb8aa3b, v109
	v_mul_f32_e32 v98, 0xbfb8aa3b, v98
	v_add_f32_e32 v99, v99, v59
	v_add_f32_e32 v90, v90, v74
	v_rcp_f32_e32 v124, v124
	v_add_f32_e32 v125, 1.0, v125
	v_add_f32_e32 v114, 1.0, v114
	v_exp_f32_e32 v109, v109
	v_exp_f32_e32 v98, v98
	v_mul_f32_e32 v99, 0xbfb8aa3b, v99
	v_mul_f32_e32 v90, 0xbfb8aa3b, v90
	v_add_f32_e32 v91, v91, v75
	v_mul_f32_e32 v138, v138, v130
	v_add_f32_e32 v130, v139, v67
	v_rcp_f32_e32 v125, v125
	v_rcp_f32_e32 v114, v114
	v_add_f32_e32 v115, 1.0, v115
	v_add_f32_e32 v106, 1.0, v106
	v_exp_f32_e32 v99, v99
	v_exp_f32_e32 v90, v90
	v_mul_f32_e32 v91, 0xbfb8aa3b, v91
	v_add_f32_e32 v92, v92, v76
	v_mul_f32_e32 v139, v130, v131
	v_add_f32_e32 v131, v132, v60
	v_mul_f32_e32 v122, v126, v122
	v_add_f32_e32 v126, v127, v79
	v_rcp_f32_e32 v115, v115
	v_rcp_f32_e32 v106, v106
	v_add_f32_e32 v107, 1.0, v107
	v_exp_f32_e32 v91, v91
	v_mul_f32_e32 v92, 0xbfb8aa3b, v92
	v_add_f32_e32 v93, v93, v77
	v_add_f32_e32 v82, v82, v58
	v_mul_f32_e32 v131, 0xbfb8aa3b, v131
	v_mul_f32_e32 v123, v126, v123
	v_add_f32_e32 v126, v128, v80
	v_rcp_f32_e32 v107, v107
	v_add_f32_e32 v108, 1.0, v108
	v_exp_f32_e32 v92, v92
	v_mul_f32_e32 v93, 0xbfb8aa3b, v93
	v_mul_f32_e32 v82, 0xbfb8aa3b, v82
	v_add_f32_e32 v83, v83, v59
	v_add_f32_e32 v50, v50, v58
	v_exp_f32_e32 v131, v131
	v_mul_f32_e32 v124, v126, v124
	v_add_f32_e32 v126, v129, v81
	v_add_f32_e32 v118, v118, v66
	v_rcp_f32_e32 v108, v108
	v_add_f32_e32 v109, 1.0, v109
	v_add_f32_e32 v98, 1.0, v98
	v_exp_f32_e32 v93, v93
	v_exp_f32_e32 v82, v82
	v_mul_f32_e32 v83, 0xbfb8aa3b, v83
	v_mul_f32_e32 v50, 0xbfb8aa3b, v50
	v_add_f32_e32 v51, v51, v59
	v_mul_f32_e32 v125, v126, v125
	v_mul_f32_e32 v126, v118, v114
	v_add_f32_e32 v114, v119, v67
	v_add_f32_e32 v110, v110, v78
	v_rcp_f32_e32 v109, v109
	v_rcp_f32_e32 v98, v98
	v_add_f32_e32 v99, 1.0, v99
	v_add_f32_e32 v90, 1.0, v90
	v_exp_f32_e32 v83, v83
	v_exp_f32_e32 v50, v50
	v_mul_f32_e32 v51, 0xbfb8aa3b, v51
	v_add_f32_e32 v34, v34, v58
	v_mul_f32_e32 v127, v114, v115
	v_add_f32_e32 v115, v116, v60
	v_mul_f32_e32 v106, v110, v106
	v_add_f32_e32 v110, v111, v79
	v_rcp_f32_e32 v99, v99
	v_rcp_f32_e32 v90, v90
	v_add_f32_e32 v91, 1.0, v91
	v_exp_f32_e32 v51, v51
	v_mul_f32_e32 v34, 0xbfb8aa3b, v34
	v_add_f32_e32 v35, v35, v59
	v_mul_f32_e32 v115, 0xbfb8aa3b, v115
	v_mul_f32_e32 v107, v110, v107
	v_add_f32_e32 v110, v112, v80
	v_rcp_f32_e32 v91, v91
	v_add_f32_e32 v92, 1.0, v92
	v_exp_f32_e32 v34, v34
	v_mul_f32_e32 v35, 0xbfb8aa3b, v35
	v_add_f32_e32 v18, v18, v58
	v_add_f32_e32 v131, 1.0, v131
	v_exp_f32_e32 v115, v115
	v_mul_f32_e32 v108, v110, v108
	v_add_f32_e32 v110, v113, v81
	v_add_f32_e32 v102, v102, v66
	v_rcp_f32_e32 v92, v92
	v_add_f32_e32 v93, 1.0, v93
	v_add_f32_e32 v82, 1.0, v82
	v_exp_f32_e32 v35, v35
	v_mul_f32_e32 v18, 0xbfb8aa3b, v18
	v_add_f32_e32 v19, v19, v59
	v_rcp_f32_e32 v131, v131
	v_mul_f32_e32 v109, v110, v109
	v_mul_f32_e32 v110, v102, v98
	v_add_f32_e32 v98, v103, v67
	v_add_f32_e32 v94, v94, v78
	v_rcp_f32_e32 v93, v93
	v_rcp_f32_e32 v82, v82
	v_add_f32_e32 v83, 1.0, v83
	v_add_f32_e32 v50, 1.0, v50
	v_exp_f32_e32 v18, v18
	v_mul_f32_e32 v19, 0xbfb8aa3b, v19
	v_add_f32_e32 v2, v2, v58
	v_mul_f32_e32 v111, v98, v99
	v_add_f32_e32 v99, v100, v60
	v_mul_f32_e32 v90, v94, v90
	v_add_f32_e32 v94, v95, v79
	v_rcp_f32_e32 v83, v83
	v_rcp_f32_e32 v50, v50
	v_add_f32_e32 v51, 1.0, v51
	v_exp_f32_e32 v19, v19
	v_mul_f32_e32 v2, 0xbfb8aa3b, v2
	v_add_f32_e32 v3, v3, v59
	v_add_f32_e32 v134, v134, v74
	v_mul_f32_e32 v99, 0xbfb8aa3b, v99
	v_mul_f32_e32 v91, v94, v91
	v_add_f32_e32 v94, v96, v80
	v_rcp_f32_e32 v51, v51
	v_add_f32_e32 v34, 1.0, v34
	v_exp_f32_e32 v2, v2
	v_mul_f32_e32 v3, 0xbfb8aa3b, v3
	v_mul_f32_e32 v134, 0xbfb8aa3b, v134
	v_add_f32_e32 v135, v135, v75
	v_add_f32_e32 v130, v140, v68
	v_add_f32_e32 v115, 1.0, v115
	v_exp_f32_e32 v99, v99
	v_mul_f32_e32 v92, v94, v92
	v_add_f32_e32 v94, v97, v81
	v_add_f32_e32 v86, v86, v66
	v_rcp_f32_e32 v34, v34
	v_add_f32_e32 v35, 1.0, v35
	v_exp_f32_e32 v3, v3
	v_exp_f32_e32 v134, v134
	v_mul_f32_e32 v135, 0xbfb8aa3b, v135
	v_add_f32_e32 v136, v136, v76
	v_mul_f32_e32 v140, v130, v131
	v_add_f32_e32 v131, v133, v61
	v_rcp_f32_e32 v115, v115
	v_mul_f32_e32 v93, v94, v93
	v_mul_f32_e32 v94, v86, v82
	v_add_f32_e32 v82, v87, v67
	v_add_f32_e32 v54, v54, v66
	v_rcp_f32_e32 v35, v35
	v_add_f32_e32 v18, 1.0, v18
	v_exp_f32_e32 v135, v135
	v_mul_f32_e32 v136, 0xbfb8aa3b, v136
	v_add_f32_e32 v137, v137, v77
	v_mul_f32_e32 v131, 0xbfb8aa3b, v131
	v_mul_f32_e32 v95, v82, v83
	v_add_f32_e32 v83, v84, v60
	v_mul_f32_e32 v54, v54, v50
	v_add_f32_e32 v50, v55, v67
	v_rcp_f32_e32 v18, v18
	v_add_f32_e32 v19, 1.0, v19
	v_exp_f32_e32 v136, v136
	v_mul_f32_e32 v137, 0xbfb8aa3b, v137
	v_exp_f32_e32 v131, v131
	v_mul_f32_e32 v83, 0xbfb8aa3b, v83
	v_mul_f32_e32 v55, v50, v51
	v_add_f32_e32 v51, v52, v60
	v_add_f32_e32 v38, v38, v66
	v_rcp_f32_e32 v19, v19
	v_add_f32_e32 v2, 1.0, v2
	v_exp_f32_e32 v137, v137
	v_add_f32_e32 v114, v120, v68
	v_add_f32_e32 v99, 1.0, v99
	v_exp_f32_e32 v83, v83
	v_mul_f32_e32 v51, 0xbfb8aa3b, v51
	v_mul_f32_e32 v38, v38, v34
	v_add_f32_e32 v34, v39, v67
	v_rcp_f32_e32 v2, v2
	v_add_f32_e32 v3, 1.0, v3
	v_add_f32_e32 v134, 1.0, v134
	v_mul_f32_e32 v120, v114, v115
	v_add_f32_e32 v115, v117, v61
	v_rcp_f32_e32 v99, v99
	v_exp_f32_e32 v51, v51
	v_mul_f32_e32 v39, v34, v35
	v_add_f32_e32 v35, v36, v60
	v_add_f32_e32 v22, v22, v66
	v_rcp_f32_e32 v3, v3
	v_rcp_f32_e32 v134, v134
	v_add_f32_e32 v135, 1.0, v135
	v_mul_f32_e32 v115, 0xbfb8aa3b, v115
	v_mul_f32_e32 v35, 0xbfb8aa3b, v35
	v_mul_f32_e32 v22, v22, v18
	v_add_f32_e32 v18, v23, v67
	v_rcp_f32_e32 v135, v135
	v_add_f32_e32 v136, 1.0, v136
	v_add_f32_e32 v131, 1.0, v131
	v_exp_f32_e32 v115, v115
	v_exp_f32_e32 v35, v35
	v_mul_f32_e32 v23, v18, v19
	v_add_f32_e32 v19, v20, v60
	v_add_f32_e32 v6, v6, v66
	v_rcp_f32_e32 v136, v136
	v_add_f32_e32 v137, 1.0, v137
	v_rcp_f32_e32 v131, v131
	v_add_f32_e32 v98, v104, v68
	v_add_f32_e32 v83, 1.0, v83
	v_mul_f32_e32 v19, 0xbfb8aa3b, v19
	v_mul_f32_e32 v6, v6, v2
	v_add_f32_e32 v2, v7, v67
	v_add_f32_e32 v142, v142, v78
	v_rcp_f32_e32 v137, v137
	v_mul_f32_e32 v104, v98, v99
	v_add_f32_e32 v99, v101, v61
	v_rcp_f32_e32 v83, v83
	v_add_f32_e32 v51, 1.0, v51
	v_exp_f32_e32 v19, v19
	v_mul_f32_e32 v7, v2, v3
	v_add_f32_e32 v3, v4, v60
	v_mul_f32_e32 v134, v142, v134
	v_add_f32_e32 v142, v143, v79
	v_mul_f32_e32 v99, 0xbfb8aa3b, v99
	v_rcp_f32_e32 v51, v51
	v_mul_f32_e32 v3, 0xbfb8aa3b, v3
	v_mul_f32_e32 v135, v142, v135
	v_add_f32_e32 v142, v144, v80
	v_add_f32_e32 v130, v141, v69
	v_add_f32_e32 v115, 1.0, v115
	v_exp_f32_e32 v99, v99
	v_add_f32_e32 v62, v62, v74
	v_add_f32_e32 v35, 1.0, v35
	v_exp_f32_e32 v3, v3
	v_mul_f32_e32 v136, v142, v136
	v_add_f32_e32 v142, v145, v81
	v_mul_f32_e32 v141, v130, v131
	v_lshl_add_u64 v[130:131], v[172:173], 0, v[182:183]
	v_cvt_pk_bf16_f32 v132, v134, v135
	v_rcp_f32_e32 v115, v115
	v_add_f32_e32 v82, v88, v68
	v_mul_f32_e32 v62, 0xbfb8aa3b, v62
	v_add_f32_e32 v63, v63, v75
	v_rcp_f32_e32 v35, v35
	v_mul_f32_e32 v137, v142, v137
	v_cvt_pk_bf16_f32 v133, v136, v137
	v_cvt_pk_bf16_f32 v134, v138, v139
	v_cvt_pk_bf16_f32 v135, v140, v141
	global_store_dwordx4 v[130:131], v[132:135], off
	v_mul_f32_e32 v88, v82, v83
	v_add_f32_e32 v83, v85, v61
	v_or_b32_e32 v132, 16, v174
	v_exp_f32_e32 v62, v62
	v_mul_f32_e32 v63, 0xbfb8aa3b, v63
	v_add_f32_e32 v64, v64, v76
	v_add_f32_e32 v50, v56, v68
	v_add_f32_e32 v42, v42, v74
	v_add_f32_e32 v19, 1.0, v19
	v_ashrrev_i32_e32 v133, 31, v132
	v_mul_f32_e32 v83, 0xbfb8aa3b, v83
	v_exp_f32_e32 v63, v63
	v_mul_f32_e32 v64, 0xbfb8aa3b, v64
	v_add_f32_e32 v65, v65, v77
	v_mul_f32_e32 v56, v50, v51
	v_add_f32_e32 v51, v53, v61
	v_mul_f32_e32 v42, 0xbfb8aa3b, v42
	v_add_f32_e32 v43, v43, v75
	v_rcp_f32_e32 v19, v19
	v_lshlrev_b64 v[132:133], 11, v[132:133]
	v_add_f32_e32 v114, v121, v69
	v_add_f32_e32 v99, 1.0, v99
	v_exp_f32_e32 v83, v83
	v_exp_f32_e32 v64, v64
	v_mul_f32_e32 v65, 0xbfb8aa3b, v65
	v_mul_f32_e32 v51, 0xbfb8aa3b, v51
	v_exp_f32_e32 v42, v42
	v_mul_f32_e32 v43, 0xbfb8aa3b, v43
	v_add_f32_e32 v44, v44, v76
	v_add_f32_e32 v34, v40, v68
	v_add_f32_e32 v26, v26, v74
	v_add_f32_e32 v3, 1.0, v3
	v_mul_f32_e32 v117, v114, v115
	v_lshl_add_u64 v[118:119], v[172:173], 0, v[132:133]
	v_cvt_pk_bf16_f32 v114, v122, v123
	v_rcp_f32_e32 v99, v99
	v_exp_f32_e32 v65, v65
	v_exp_f32_e32 v51, v51
	v_exp_f32_e32 v43, v43
	v_mul_f32_e32 v44, 0xbfb8aa3b, v44
	v_add_f32_e32 v45, v45, v77
	v_mul_f32_e32 v40, v34, v35
	v_add_f32_e32 v35, v37, v61
	v_mul_f32_e32 v26, 0xbfb8aa3b, v26
	v_add_f32_e32 v27, v27, v75
	v_rcp_f32_e32 v3, v3
	v_cvt_pk_bf16_f32 v115, v124, v125
	v_cvt_pk_bf16_f32 v116, v126, v127
	v_cvt_pk_bf16_f32 v117, v120, v117
	global_store_dwordx4 v[118:119], v[114:117], off
	v_add_f32_e32 v62, 1.0, v62
	v_exp_f32_e32 v44, v44
	v_or_b32_e32 v114, 32, v174
	v_mul_f32_e32 v45, 0xbfb8aa3b, v45
	v_mul_f32_e32 v35, 0xbfb8aa3b, v35
	v_exp_f32_e32 v26, v26
	v_mul_f32_e32 v27, 0xbfb8aa3b, v27
	v_add_f32_e32 v28, v28, v76
	v_add_f32_e32 v18, v24, v68
	v_add_f32_e32 v10, v10, v74
	v_ashrrev_i32_e32 v115, 31, v114
	v_rcp_f32_e32 v62, v62
	v_add_f32_e32 v63, 1.0, v63
	v_exp_f32_e32 v45, v45
	v_exp_f32_e32 v35, v35
	v_exp_f32_e32 v27, v27
	v_mul_f32_e32 v28, 0xbfb8aa3b, v28
	v_add_f32_e32 v29, v29, v77
	v_mul_f32_e32 v24, v18, v19
	v_add_f32_e32 v19, v21, v61
	v_mul_f32_e32 v10, 0xbfb8aa3b, v10
	v_add_f32_e32 v11, v11, v75
	v_lshlrev_b64 v[114:115], 11, v[114:115]
	v_add_f32_e32 v98, v105, v69
	v_add_f32_e32 v83, 1.0, v83
	v_rcp_f32_e32 v63, v63
	v_add_f32_e32 v64, 1.0, v64
	v_add_f32_e32 v42, 1.0, v42
	v_exp_f32_e32 v28, v28
	v_mul_f32_e32 v29, 0xbfb8aa3b, v29
	v_mul_f32_e32 v19, 0xbfb8aa3b, v19
	v_exp_f32_e32 v10, v10
	v_mul_f32_e32 v11, 0xbfb8aa3b, v11
	v_add_f32_e32 v12, v12, v76
	v_add_f32_e32 v2, v8, v68
	v_mul_f32_e32 v101, v98, v99
	v_lshl_add_u64 v[102:103], v[172:173], 0, v[114:115]
	v_cvt_pk_bf16_f32 v98, v106, v107
	v_rcp_f32_e32 v83, v83
	v_rcp_f32_e32 v64, v64
	v_add_f32_e32 v65, 1.0, v65
	v_add_f32_e32 v51, 1.0, v51
	v_rcp_f32_e32 v42, v42
	v_add_f32_e32 v43, 1.0, v43
	v_exp_f32_e32 v29, v29
	v_exp_f32_e32 v19, v19
	v_exp_f32_e32 v11, v11
	v_mul_f32_e32 v12, 0xbfb8aa3b, v12
	v_add_f32_e32 v13, v13, v77
	v_mul_f32_e32 v8, v2, v3
	v_add_f32_e32 v3, v5, v61
	v_cvt_pk_bf16_f32 v99, v108, v109
	v_cvt_pk_bf16_f32 v100, v110, v111
	v_cvt_pk_bf16_f32 v101, v104, v101
	global_store_dwordx4 v[102:103], v[98:101], off
	v_add_f32_e32 v70, v70, v78
	v_rcp_f32_e32 v65, v65
	v_or_b32_e32 v98, 48, v174
	v_rcp_f32_e32 v51, v51
	v_rcp_f32_e32 v43, v43
	v_add_f32_e32 v44, 1.0, v44
	v_add_f32_e32 v26, 1.0, v26
	v_exp_f32_e32 v12, v12
	v_mul_f32_e32 v13, 0xbfb8aa3b, v13
	v_mul_f32_e32 v3, 0xbfb8aa3b, v3
	v_ashrrev_i32_e32 v99, 31, v98
	v_mul_f32_e32 v62, v70, v62
	v_add_f32_e32 v70, v71, v79
	v_rcp_f32_e32 v44, v44
	v_add_f32_e32 v45, 1.0, v45
	v_add_f32_e32 v35, 1.0, v35
	v_rcp_f32_e32 v26, v26
	v_add_f32_e32 v27, 1.0, v27
	v_exp_f32_e32 v13, v13
	v_exp_f32_e32 v3, v3
	v_lshlrev_b64 v[98:99], 11, v[98:99]
	v_add_f32_e32 v82, v89, v69
	v_mul_f32_e32 v63, v70, v63
	v_add_f32_e32 v70, v72, v80
	v_add_f32_e32 v46, v46, v78
	v_rcp_f32_e32 v45, v45
	v_rcp_f32_e32 v35, v35
	v_rcp_f32_e32 v27, v27
	v_add_f32_e32 v28, 1.0, v28
	v_add_f32_e32 v10, 1.0, v10
	v_mul_f32_e32 v85, v82, v83
	v_lshl_add_u64 v[86:87], v[172:173], 0, v[98:99]
	v_mul_f32_e32 v64, v70, v64
	v_add_f32_e32 v70, v73, v81
	v_add_f32_e32 v50, v57, v69
	v_mul_f32_e32 v42, v46, v42
	v_add_f32_e32 v46, v47, v79
	v_rcp_f32_e32 v28, v28
	v_add_f32_e32 v29, 1.0, v29
	v_add_f32_e32 v19, 1.0, v19
	v_rcp_f32_e32 v10, v10
	v_add_f32_e32 v11, 1.0, v11
	v_cvt_pk_bf16_f32 v82, v90, v91
	v_cvt_pk_bf16_f32 v83, v92, v93
	v_cvt_pk_bf16_f32 v84, v94, v95
	v_cvt_pk_bf16_f32 v85, v88, v85
	global_store_dwordx4 v[86:87], v[82:85], off
	v_mul_f32_e32 v65, v70, v65
	v_mul_f32_e32 v53, v50, v51
	v_cvt_pk_bf16_f32 v50, v62, v63
	v_cvt_pk_bf16_f32 v51, v64, v65
	v_cvt_pk_bf16_f32 v52, v54, v55
	v_add_co_u32_e32 v54, vcc, s67, v130
	v_mul_f32_e32 v43, v46, v43
	v_add_f32_e32 v46, v48, v80
	v_add_f32_e32 v30, v30, v78
	v_rcp_f32_e32 v29, v29
	v_rcp_f32_e32 v19, v19
	v_rcp_f32_e32 v11, v11
	v_add_f32_e32 v12, 1.0, v12
	v_addc_co_u32_e32 v55, vcc, 0, v131, vcc
	v_mul_f32_e32 v44, v46, v44
	v_add_f32_e32 v46, v49, v81
	v_add_f32_e32 v34, v41, v69
	v_mul_f32_e32 v26, v30, v26
	v_add_f32_e32 v30, v31, v79
	v_rcp_f32_e32 v12, v12
	v_add_f32_e32 v13, 1.0, v13
	v_add_f32_e32 v3, 1.0, v3
	v_cvt_pk_bf16_f32 v53, v56, v53
	global_store_dwordx4 v[54:55], v[50:53], off
	v_mul_f32_e32 v45, v46, v45
	v_mul_f32_e32 v37, v34, v35
	v_cvt_pk_bf16_f32 v34, v42, v43
	v_cvt_pk_bf16_f32 v35, v44, v45
	v_cvt_pk_bf16_f32 v36, v38, v39
	v_add_co_u32_e32 v38, vcc, s68, v130
	v_mul_f32_e32 v27, v30, v27
	v_add_f32_e32 v30, v32, v80
	v_add_f32_e32 v14, v14, v78
	v_rcp_f32_e32 v13, v13
	v_rcp_f32_e32 v3, v3
	v_addc_co_u32_e32 v39, vcc, 0, v131, vcc
	v_mul_f32_e32 v28, v30, v28
	v_add_f32_e32 v30, v33, v81
	v_add_f32_e32 v18, v25, v69
	v_mul_f32_e32 v10, v14, v10
	v_add_f32_e32 v14, v15, v79
	v_cvt_pk_bf16_f32 v37, v40, v37
	global_store_dwordx4 v[38:39], v[34:37], off
	v_mul_f32_e32 v29, v30, v29
	v_mul_f32_e32 v21, v18, v19
	v_cvt_pk_bf16_f32 v18, v26, v27
	v_cvt_pk_bf16_f32 v19, v28, v29
	v_cvt_pk_bf16_f32 v20, v22, v23
	v_add_co_u32_e32 v22, vcc, s2, v130
	v_mul_f32_e32 v11, v14, v11
	v_add_f32_e32 v14, v16, v80
	v_addc_co_u32_e32 v23, vcc, 0, v131, vcc
	v_mul_f32_e32 v12, v14, v12
	v_add_f32_e32 v14, v17, v81
	v_add_f32_e32 v2, v9, v69
	v_cvt_pk_bf16_f32 v21, v24, v21
	global_store_dwordx4 v[22:23], v[18:21], off
	v_mul_f32_e32 v13, v14, v13
	v_mul_f32_e32 v5, v2, v3
	v_cvt_pk_bf16_f32 v2, v10, v11
	v_cvt_pk_bf16_f32 v3, v12, v13
	v_cvt_pk_bf16_f32 v4, v6, v7
	v_add_co_u32_e32 v6, vcc, 0x58000, v130
	s_mov_b32 s2, s48
	s_nop 0
	v_addc_co_u32_e32 v7, vcc, 0, v131, vcc
	s_and_b64 vcc, exec, s[38:39]
	v_cvt_pk_bf16_f32 v5, v8, v5
	global_store_dwordx4 v[6:7], v[2:5], off
	s_cbranch_vccz .LBB0_88
	s_waitcnt vmcnt(8)
	s_cmpk_gt_u32 s35, 0xff
	s_cbranch_scc1 .LBB0_99
	s_barrier

.Lkprio_3:
.LBB0_260:
	s_add_u32 s22, s0, 0xfffc0080
	s_addc_u32 s23, s1, -1
	s_add_i32 s60, 0, 0x10000
	v_add_u32_e32 v142, s60, v178
	ds_read_b128 v[130:133], v142
	ds_read_b128 v[134:137], v142 offset:1024
	ds_read_b128 v[138:141], v142 offset:2048
	ds_read_b128 v[142:145], v142 offset:3072
	s_cmp_eq_u32 s59, 12
	s_cselect_b32 s47, s35, s23
	s_cselect_b32 s46, s55, s22
	s_cselect_b32 s23, s31, s58
	s_cselect_b32 s22, s56, s57
	v_lshl_add_u64 v[186:187], s[0:1], 0, v[168:169]
	s_add_i32 m0, s27, 0xc000
	ds_read_b128 v[172:175], v180
	ds_read_b128 v[182:185], v180 offset:1024
	ds_read_b128 v[206:209], v180 offset:2048
	ds_read_b128 v[210:213], v180 offset:3072
	ds_read_b128 v[214:217], v180 offset:4096
	ds_read_b128 v[218:221], v180 offset:5120
	ds_read_b128 v[222:225], v180 offset:6144
	ds_read_b128 v[226:229], v180 offset:7168
	global_load_lds_dwordx4 v[186:187], off
	s_add_i32 m0, s27, 0xe000
	v_lshl_add_u64 v[186:187], s[0:1], 0, v[170:171]
	global_load_lds_dwordx4 v[186:187], off
	s_waitcnt lgkmcnt(8)
	s_barrier
	s_waitcnt lgkmcnt(7)
	v_mfma_f32_16x16x32_bf16 v[126:129], v[130:133], v[172:175], v[126:129]
	v_mfma_f32_16x16x32_bf16 v[122:125], v[138:141], v[172:175], v[122:125]
	s_waitcnt lgkmcnt(5)
	v_mfma_f32_16x16x32_bf16 v[110:113], v[130:133], v[206:209], v[110:113]
	v_mfma_f32_16x16x32_bf16 v[106:109], v[138:141], v[206:209], v[106:109]
	s_waitcnt lgkmcnt(3)
	v_mfma_f32_16x16x32_bf16 v[94:97], v[130:133], v[214:217], v[94:97]
	v_mfma_f32_16x16x32_bf16 v[90:93], v[138:141], v[214:217], v[90:93]
	s_waitcnt lgkmcnt(1)
	v_mfma_f32_16x16x32_bf16 v[78:81], v[130:133], v[222:225], v[78:81]
	v_mfma_f32_16x16x32_bf16 v[74:77], v[138:141], v[222:225], v[74:77]
	v_mfma_f32_16x16x32_bf16 v[126:129], v[134:137], v[182:185], v[126:129]
	v_mfma_f32_16x16x32_bf16 v[122:125], v[142:145], v[182:185], v[122:125]
	v_mfma_f32_16x16x32_bf16 v[110:113], v[134:137], v[210:213], v[110:113]
	v_mfma_f32_16x16x32_bf16 v[106:109], v[142:145], v[210:213], v[106:109]
	v_mfma_f32_16x16x32_bf16 v[94:97], v[134:137], v[218:221], v[94:97]
	v_mfma_f32_16x16x32_bf16 v[90:93], v[142:145], v[218:221], v[90:93]
	s_waitcnt lgkmcnt(0)
	v_mfma_f32_16x16x32_bf16 v[78:81], v[134:137], v[226:229], v[78:81]
	v_mfma_f32_16x16x32_bf16 v[74:77], v[142:145], v[226:229], v[74:77]
	s_barrier
	s_add_i32 s62, 0, 0x14000
	s_add_i32 s60, s60, s25
	v_add_u32_e32 v181, s62, v178
	v_lshl_add_u64 v[186:187], s[22:23], 0, v[0:1]
	s_mov_b32 m0, s60
	ds_read_b128 v[230:233], v181
	ds_read_b128 v[234:237], v181 offset:1024
	ds_read_b128 v[238:241], v181 offset:2048
	ds_read_b128 v[242:245], v181 offset:3072
	global_load_lds_dwordx4 v[186:187], off
	s_add_i32 m0, s60, 0x2000
	v_lshl_add_u64 v[246:247], s[22:23], 0, v[162:163]
	global_load_lds_dwordx4 v[246:247], off
	s_barrier
	s_waitcnt lgkmcnt(3)
	v_mfma_f32_16x16x32_bf16 v[118:121], v[230:233], v[172:175], v[118:121]
	s_waitcnt lgkmcnt(1)
	v_mfma_f32_16x16x32_bf16 v[114:117], v[238:241], v[172:175], v[114:117]
	v_mfma_f32_16x16x32_bf16 v[102:105], v[230:233], v[206:209], v[102:105]
	v_mfma_f32_16x16x32_bf16 v[98:101], v[238:241], v[206:209], v[98:101]
	v_mfma_f32_16x16x32_bf16 v[86:89], v[230:233], v[214:217], v[86:89]
	v_mfma_f32_16x16x32_bf16 v[82:85], v[238:241], v[214:217], v[82:85]
	v_mfma_f32_16x16x32_bf16 v[70:73], v[230:233], v[222:225], v[70:73]
	v_mfma_f32_16x16x32_bf16 v[66:69], v[238:241], v[222:225], v[66:69]
	v_mfma_f32_16x16x32_bf16 v[118:121], v[234:237], v[182:185], v[118:121]
	s_waitcnt lgkmcnt(0)
	v_mfma_f32_16x16x32_bf16 v[114:117], v[242:245], v[182:185], v[114:117]
	v_mfma_f32_16x16x32_bf16 v[102:105], v[234:237], v[210:213], v[102:105]
	v_mfma_f32_16x16x32_bf16 v[98:101], v[242:245], v[210:213], v[98:101]
	v_mfma_f32_16x16x32_bf16 v[86:89], v[234:237], v[218:221], v[86:89]
	v_mfma_f32_16x16x32_bf16 v[82:85], v[242:245], v[218:221], v[82:85]
	v_mfma_f32_16x16x32_bf16 v[70:73], v[234:237], v[226:229], v[70:73]
	v_mfma_f32_16x16x32_bf16 v[66:69], v[242:245], v[226:229], v[66:69]
	s_barrier
	s_mov_b32 m0, s27
	v_lshl_add_u64 v[248:249], s[46:47], 0, v[166:167]
	ds_read_b128 v[172:175], v180 offset:16384
	ds_read_b128 v[182:185], v180 offset:17408
	ds_read_b128 v[206:209], v180 offset:18432
	ds_read_b128 v[210:213], v180 offset:19456
	ds_read_b128 v[214:217], v180 offset:20480
	ds_read_b128 v[218:221], v180 offset:21504
	ds_read_b128 v[222:225], v180 offset:22528
	ds_read_b128 v[226:229], v180 offset:23552
	global_load_lds_dwordx4 v[248:249], off
	s_mov_b32 m0, s45
	v_lshl_add_u64 v[250:251], s[46:47], 0, v[164:165]
	global_load_lds_dwordx4 v[250:251], off
	s_barrier
	s_waitcnt lgkmcnt(7)
	v_mfma_f32_16x16x32_bf16 v[62:65], v[130:133], v[172:175], v[62:65]
	v_mfma_f32_16x16x32_bf16 v[58:61], v[138:141], v[172:175], v[58:61]
	s_waitcnt lgkmcnt(5)
	v_mfma_f32_16x16x32_bf16 v[50:53], v[130:133], v[206:209], v[50:53]
	v_mfma_f32_16x16x32_bf16 v[42:45], v[138:141], v[206:209], v[42:45]
	s_waitcnt lgkmcnt(3)
	v_mfma_f32_16x16x32_bf16 v[34:37], v[130:133], v[214:217], v[34:37]
	v_mfma_f32_16x16x32_bf16 v[26:29], v[138:141], v[214:217], v[26:29]
	s_waitcnt lgkmcnt(1)
	v_mfma_f32_16x16x32_bf16 v[18:21], v[130:133], v[222:225], v[18:21]
	v_mfma_f32_16x16x32_bf16 v[10:13], v[138:141], v[222:225], v[10:13]
	v_mfma_f32_16x16x32_bf16 v[62:65], v[134:137], v[182:185], v[62:65]
	v_mfma_f32_16x16x32_bf16 v[58:61], v[142:145], v[182:185], v[58:61]
	v_mfma_f32_16x16x32_bf16 v[50:53], v[134:137], v[210:213], v[50:53]
	v_mfma_f32_16x16x32_bf16 v[42:45], v[142:145], v[210:213], v[42:45]
	v_mfma_f32_16x16x32_bf16 v[34:37], v[134:137], v[218:221], v[34:37]
	v_mfma_f32_16x16x32_bf16 v[26:29], v[142:145], v[218:221], v[26:29]
	s_waitcnt lgkmcnt(0)
	v_mfma_f32_16x16x32_bf16 v[18:21], v[134:137], v[226:229], v[18:21]
	v_mfma_f32_16x16x32_bf16 v[10:13], v[142:145], v[226:229], v[10:13]
	s_barrier
	s_add_u32 s60, s22, 0x40000
	s_addc_u32 s61, s23, 0
	s_add_i32 s62, s62, s25
	s_mov_b32 m0, s62
	s_nop 0
	global_load_lds_dwordx4 v0, s[60:61]
	s_add_i32 m0, s62, 0x2000
	v_lshl_add_u64 v[130:131], s[60:61], 0, v[162:163]
	global_load_lds_dwordx4 v[130:131], off
	s_waitcnt vmcnt(6)
	s_barrier
	v_mfma_f32_16x16x32_bf16 v[54:57], v[230:233], v[172:175], v[54:57]
	v_mfma_f32_16x16x32_bf16 v[46:49], v[238:241], v[172:175], v[46:49]
	v_mfma_f32_16x16x32_bf16 v[38:41], v[230:233], v[206:209], v[38:41]
	v_mfma_f32_16x16x32_bf16 v[30:33], v[238:241], v[206:209], v[30:33]
	v_mfma_f32_16x16x32_bf16 v[22:25], v[230:233], v[214:217], v[22:25]
	v_mfma_f32_16x16x32_bf16 v[14:17], v[238:241], v[214:217], v[14:17]
	v_mfma_f32_16x16x32_bf16 v[6:9], v[230:233], v[222:225], v[6:9]
	v_mfma_f32_16x16x32_bf16 v[2:5], v[238:241], v[222:225], v[2:5]
	v_mfma_f32_16x16x32_bf16 v[54:57], v[234:237], v[182:185], v[54:57]
	v_mfma_f32_16x16x32_bf16 v[46:49], v[242:245], v[182:185], v[46:49]
	v_mfma_f32_16x16x32_bf16 v[38:41], v[234:237], v[210:213], v[38:41]
	v_mfma_f32_16x16x32_bf16 v[30:33], v[242:245], v[210:213], v[30:33]
	v_mfma_f32_16x16x32_bf16 v[22:25], v[234:237], v[218:221], v[22:25]
	v_mfma_f32_16x16x32_bf16 v[14:17], v[242:245], v[218:221], v[14:17]
	v_mfma_f32_16x16x32_bf16 v[6:9], v[234:237], v[226:229], v[6:9]
	v_mfma_f32_16x16x32_bf16 v[2:5], v[242:245], v[226:229], v[2:5]
	s_barrier
	s_add_i32 s60, 0, 0x18000
	v_add_u32_e32 v142, s60, v178
	ds_read_b128 v[130:133], v142
	ds_read_b128 v[134:137], v142 offset:1024
	ds_read_b128 v[138:141], v142 offset:2048
	ds_read_b128 v[142:145], v142 offset:3072
	s_add_u32 s46, s46, 0x40000
	s_addc_u32 s47, s47, 0
	s_mov_b32 m0, s48
	v_lshl_add_u64 v[230:231], s[46:47], 0, v[166:167]
	ds_read_b128 v[172:175], v180 offset:32768
	ds_read_b128 v[182:185], v180 offset:33792
	ds_read_b128 v[206:209], v180 offset:34816
	ds_read_b128 v[210:213], v180 offset:35840
	ds_read_b128 v[214:217], v180 offset:36864
	ds_read_b128 v[218:221], v180 offset:37888
	ds_read_b128 v[222:225], v180 offset:38912
	ds_read_b128 v[226:229], v180 offset:39936
	global_load_lds_dwordx4 v[230:231], off
	s_mov_b32 m0, s49
	v_lshl_add_u64 v[230:231], s[46:47], 0, v[164:165]
	global_load_lds_dwordx4 v[230:231], off
	s_waitcnt lgkmcnt(8)
	s_barrier
	s_waitcnt lgkmcnt(7)
	v_mfma_f32_16x16x32_bf16 v[126:129], v[130:133], v[172:175], v[126:129]
	v_mfma_f32_16x16x32_bf16 v[122:125], v[138:141], v[172:175], v[122:125]
	s_waitcnt lgkmcnt(5)
	v_mfma_f32_16x16x32_bf16 v[110:113], v[130:133], v[206:209], v[110:113]
	v_mfma_f32_16x16x32_bf16 v[106:109], v[138:141], v[206:209], v[106:109]
	s_waitcnt lgkmcnt(3)
	v_mfma_f32_16x16x32_bf16 v[94:97], v[130:133], v[214:217], v[94:97]
	v_mfma_f32_16x16x32_bf16 v[90:93], v[138:141], v[214:217], v[90:93]
	s_waitcnt lgkmcnt(1)
	v_mfma_f32_16x16x32_bf16 v[78:81], v[130:133], v[222:225], v[78:81]
	v_mfma_f32_16x16x32_bf16 v[74:77], v[138:141], v[222:225], v[74:77]
	v_mfma_f32_16x16x32_bf16 v[126:129], v[134:137], v[182:185], v[126:129]
	v_mfma_f32_16x16x32_bf16 v[122:125], v[142:145], v[182:185], v[122:125]
	v_mfma_f32_16x16x32_bf16 v[110:113], v[134:137], v[210:213], v[110:113]
	v_mfma_f32_16x16x32_bf16 v[106:109], v[142:145], v[210:213], v[106:109]
	v_mfma_f32_16x16x32_bf16 v[94:97], v[134:137], v[218:221], v[94:97]
	v_mfma_f32_16x16x32_bf16 v[90:93], v[142:145], v[218:221], v[90:93]
	s_waitcnt lgkmcnt(0)
	v_mfma_f32_16x16x32_bf16 v[78:81], v[134:137], v[226:229], v[78:81]
	v_mfma_f32_16x16x32_bf16 v[74:77], v[142:145], v[226:229], v[74:77]
	s_barrier
	s_add_i32 s46, 0, 0x1c000
	s_add_i32 s47, s60, s25
	v_add_u32_e32 v181, s46, v178
	v_lshl_add_u64 v[186:187], v[186:187], 0, s[94:95]
	s_mov_b32 m0, s47
	ds_read_b128 v[230:233], v181
	ds_read_b128 v[234:237], v181 offset:1024
	ds_read_b128 v[238:241], v181 offset:2048
	ds_read_b128 v[242:245], v181 offset:3072
	global_load_lds_dwordx4 v[186:187], off
	s_add_i32 m0, s47, 0x2000
	v_lshl_add_u64 v[186:187], v[246:247], 0, s[94:95]
	global_load_lds_dwordx4 v[186:187], off
	s_barrier
	s_waitcnt lgkmcnt(3)
	v_mfma_f32_16x16x32_bf16 v[118:121], v[230:233], v[172:175], v[118:121]
	s_waitcnt lgkmcnt(1)
	v_mfma_f32_16x16x32_bf16 v[114:117], v[238:241], v[172:175], v[114:117]
	v_mfma_f32_16x16x32_bf16 v[102:105], v[230:233], v[206:209], v[102:105]
	v_mfma_f32_16x16x32_bf16 v[98:101], v[238:241], v[206:209], v[98:101]
	v_mfma_f32_16x16x32_bf16 v[86:89], v[230:233], v[214:217], v[86:89]
	v_mfma_f32_16x16x32_bf16 v[82:85], v[238:241], v[214:217], v[82:85]
	v_mfma_f32_16x16x32_bf16 v[70:73], v[230:233], v[222:225], v[70:73]
	v_mfma_f32_16x16x32_bf16 v[66:69], v[238:241], v[222:225], v[66:69]
	v_mfma_f32_16x16x32_bf16 v[118:121], v[234:237], v[182:185], v[118:121]
	s_waitcnt lgkmcnt(0)
	v_mfma_f32_16x16x32_bf16 v[114:117], v[242:245], v[182:185], v[114:117]
	v_mfma_f32_16x16x32_bf16 v[102:105], v[234:237], v[210:213], v[102:105]
	v_mfma_f32_16x16x32_bf16 v[98:101], v[242:245], v[210:213], v[98:101]
	v_mfma_f32_16x16x32_bf16 v[86:89], v[234:237], v[218:221], v[86:89]
	v_mfma_f32_16x16x32_bf16 v[82:85], v[242:245], v[218:221], v[82:85]
	v_mfma_f32_16x16x32_bf16 v[70:73], v[234:237], v[226:229], v[70:73]
	v_mfma_f32_16x16x32_bf16 v[66:69], v[242:245], v[226:229], v[66:69]
	s_barrier
	s_mov_b32 m0, s51
	v_lshl_add_u64 v[186:187], v[248:249], 0, s[94:95]
	ds_read_b128 v[172:175], v180 offset:49152
	ds_read_b128 v[182:185], v180 offset:50176
	ds_read_b128 v[206:209], v180 offset:51200
	ds_read_b128 v[210:213], v180 offset:52224
	ds_read_b128 v[214:217], v180 offset:53248
	ds_read_b128 v[218:221], v180 offset:54272
	ds_read_b128 v[222:225], v180 offset:55296
	ds_read_b128 v[226:229], v180 offset:56320
	global_load_lds_dwordx4 v[186:187], off
	s_mov_b32 m0, s52
	v_lshl_add_u64 v[186:187], v[250:251], 0, s[94:95]
	global_load_lds_dwordx4 v[186:187], off
	s_barrier
	s_waitcnt lgkmcnt(7)
	v_mfma_f32_16x16x32_bf16 v[62:65], v[130:133], v[172:175], v[62:65]
	v_mfma_f32_16x16x32_bf16 v[58:61], v[138:141], v[172:175], v[58:61]
	s_waitcnt lgkmcnt(5)
	v_mfma_f32_16x16x32_bf16 v[50:53], v[130:133], v[206:209], v[50:53]
	v_mfma_f32_16x16x32_bf16 v[42:45], v[138:141], v[206:209], v[42:45]
	s_waitcnt lgkmcnt(3)
	v_mfma_f32_16x16x32_bf16 v[34:37], v[130:133], v[214:217], v[34:37]
	v_mfma_f32_16x16x32_bf16 v[26:29], v[138:141], v[214:217], v[26:29]
	s_waitcnt lgkmcnt(1)
	v_mfma_f32_16x16x32_bf16 v[18:21], v[130:133], v[222:225], v[18:21]
	v_mfma_f32_16x16x32_bf16 v[10:13], v[138:141], v[222:225], v[10:13]
	v_mfma_f32_16x16x32_bf16 v[62:65], v[134:137], v[182:185], v[62:65]
	v_mfma_f32_16x16x32_bf16 v[58:61], v[142:145], v[182:185], v[58:61]
	v_mfma_f32_16x16x32_bf16 v[50:53], v[134:137], v[210:213], v[50:53]
	v_mfma_f32_16x16x32_bf16 v[42:45], v[142:145], v[210:213], v[42:45]
	v_mfma_f32_16x16x32_bf16 v[34:37], v[134:137], v[218:221], v[34:37]
	v_mfma_f32_16x16x32_bf16 v[26:29], v[142:145], v[218:221], v[26:29]
	s_waitcnt lgkmcnt(0)
	v_mfma_f32_16x16x32_bf16 v[18:21], v[134:137], v[226:229], v[18:21]
	v_mfma_f32_16x16x32_bf16 v[10:13], v[142:145], v[226:229], v[10:13]
	s_barrier
	s_add_u32 s22, s22, 0x40080
	s_addc_u32 s23, s23, 0
	s_add_i32 s46, s46, s25
	s_mov_b32 m0, s46
	s_nop 0
	global_load_lds_dwordx4 v0, s[22:23]
	s_add_i32 m0, s46, 0x2000
	v_lshl_add_u64 v[130:131], s[22:23], 0, v[162:163]
	global_load_lds_dwordx4 v[130:131], off
	s_waitcnt vmcnt(6)
	s_barrier
	v_mfma_f32_16x16x32_bf16 v[54:57], v[230:233], v[172:175], v[54:57]
	v_mfma_f32_16x16x32_bf16 v[46:49], v[238:241], v[172:175], v[46:49]
	v_mfma_f32_16x16x32_bf16 v[38:41], v[230:233], v[206:209], v[38:41]
	v_mfma_f32_16x16x32_bf16 v[30:33], v[238:241], v[206:209], v[30:33]
	v_mfma_f32_16x16x32_bf16 v[22:25], v[230:233], v[214:217], v[22:25]
	v_mfma_f32_16x16x32_bf16 v[14:17], v[238:241], v[214:217], v[14:17]
	v_mfma_f32_16x16x32_bf16 v[6:9], v[230:233], v[222:225], v[6:9]
	v_mfma_f32_16x16x32_bf16 v[2:5], v[238:241], v[222:225], v[2:5]
	v_mfma_f32_16x16x32_bf16 v[54:57], v[234:237], v[182:185], v[54:57]
	v_mfma_f32_16x16x32_bf16 v[46:49], v[242:245], v[182:185], v[46:49]
	v_mfma_f32_16x16x32_bf16 v[38:41], v[234:237], v[210:213], v[38:41]
	v_mfma_f32_16x16x32_bf16 v[30:33], v[242:245], v[210:213], v[30:33]
	v_mfma_f32_16x16x32_bf16 v[22:25], v[234:237], v[218:221], v[22:25]
	v_mfma_f32_16x16x32_bf16 v[14:17], v[242:245], v[218:221], v[14:17]
	v_mfma_f32_16x16x32_bf16 v[6:9], v[234:237], v[226:229], v[6:9]
	v_mfma_f32_16x16x32_bf16 v[2:5], v[242:245], v[226:229], v[2:5]
	s_barrier
	s_add_i32 s59, s59, 2
	s_add_u32 s0, s0, 0x100
	s_addc_u32 s1, s1, 0
	s_add_u32 s57, s57, 0x100
	s_addc_u32 s58, s58, 0
	s_cmp_gt_u32 s59, 13
	s_cbranch_scc0 .LBB0_260
	v_lshl_or_b32 v172, s54, 8, v179
	v_ashrrev_i32_e32 v173, 31, v172
	v_cndmask_b32_e64 v131, 0, 1, s[2:3]
	v_lshl_add_u64 v[174:175], v[172:173], 2, s[8:9]
	v_mov_b32_e32 v130, 0
	v_cmp_ne_u32_e64 s[0:1], 1, v131
	s_andn2_b64 vcc, exec, s[2:3]
	v_mov_b32_e32 v134, 0
	v_mov_b32_e32 v135, 0
	v_mov_b32_e32 v136, 0
	v_mov_b32_e32 v137, 0
	s_cbranch_vccnz .LBB0_263
	global_load_dwordx4 v[134:137], v[174:175], off

.Lkprio_2:
.LBB0_331:
	s_add_u32 s22, s24, 0x100
	s_addc_u32 s23, s25, 0
	s_add_i32 s52, 0, 0x10000
	v_add_u32_e32 v140, s52, v144
	ds_read_b128 v[164:167], v140
	ds_read_b128 v[168:171], v140 offset:1024
	ds_read_b128 v[172:175], v140 offset:2048
	ds_read_b128 v[176:179], v140 offset:3072
	s_cmp_eq_u32 s51, 40
	s_cselect_b32 s29, s3, s23
	s_cselect_b32 s28, s2, s22
	s_cselect_b32 s27, s1, s41
	s_cselect_b32 s26, s0, s40
	v_lshl_add_u64 v[140:141], s[24:25], 0, v[136:137]
	s_add_i32 m0, s35, 0xc000
	ds_read_b128 v[180:183], v162
	ds_read_b128 v[184:187], v162 offset:1024
	ds_read_b128 v[206:209], v162 offset:2048
	ds_read_b128 v[210:213], v162 offset:3072
	ds_read_b128 v[214:217], v162 offset:4096
	ds_read_b128 v[218:221], v162 offset:5120
	ds_read_b128 v[222:225], v162 offset:6144
	ds_read_b128 v[226:229], v162 offset:7168
	global_load_lds_dwordx4 v[140:141], off
	s_add_i32 m0, s35, 0xe000
	v_lshl_add_u64 v[140:141], s[24:25], 0, v[138:139]
	global_load_lds_dwordx4 v[140:141], off
	s_waitcnt lgkmcnt(8)
	s_barrier
	s_waitcnt lgkmcnt(7)
	v_mfma_f32_16x16x32_bf16 v[126:129], v[164:167], v[180:183], v[126:129]
	v_mfma_f32_16x16x32_bf16 v[122:125], v[172:175], v[180:183], v[122:125]
	s_waitcnt lgkmcnt(5)
	v_mfma_f32_16x16x32_bf16 v[114:117], v[164:167], v[206:209], v[114:117]
	v_mfma_f32_16x16x32_bf16 v[106:109], v[172:175], v[206:209], v[106:109]
	s_waitcnt lgkmcnt(3)
	v_mfma_f32_16x16x32_bf16 v[98:101], v[164:167], v[214:217], v[98:101]
	v_mfma_f32_16x16x32_bf16 v[90:93], v[172:175], v[214:217], v[90:93]
	s_waitcnt lgkmcnt(1)
	v_mfma_f32_16x16x32_bf16 v[82:85], v[164:167], v[222:225], v[82:85]
	v_mfma_f32_16x16x32_bf16 v[74:77], v[172:175], v[222:225], v[74:77]
	v_mfma_f32_16x16x32_bf16 v[126:129], v[168:171], v[184:187], v[126:129]
	v_mfma_f32_16x16x32_bf16 v[122:125], v[176:179], v[184:187], v[122:125]
	v_mfma_f32_16x16x32_bf16 v[114:117], v[168:171], v[210:213], v[114:117]
	v_mfma_f32_16x16x32_bf16 v[106:109], v[176:179], v[210:213], v[106:109]
	v_mfma_f32_16x16x32_bf16 v[98:101], v[168:171], v[218:221], v[98:101]
	v_mfma_f32_16x16x32_bf16 v[90:93], v[176:179], v[218:221], v[90:93]
	s_waitcnt lgkmcnt(0)
	v_mfma_f32_16x16x32_bf16 v[82:85], v[168:171], v[226:229], v[82:85]
	v_mfma_f32_16x16x32_bf16 v[74:77], v[176:179], v[226:229], v[74:77]
	s_barrier
	s_add_i32 s53, 0, 0x14000
	v_add_u32_e32 v140, s53, v144
	s_add_i32 s24, s52, s31
	ds_read_b128 v[230:233], v140
	ds_read_b128 v[234:237], v140 offset:1024
	ds_read_b128 v[238:241], v140 offset:2048
	ds_read_b128 v[242:245], v140 offset:3072
	v_lshl_add_u64 v[140:141], s[26:27], 0, v[0:1]
	s_mov_b32 m0, s24
	v_lshl_add_u64 v[246:247], s[26:27], 0, v[130:131]
	global_load_lds_dwordx4 v[140:141], off
	s_add_i32 m0, s24, 0x2000
	s_nop 0
	global_load_lds_dwordx4 v[246:247], off
	s_barrier
	s_waitcnt lgkmcnt(3)
	v_mfma_f32_16x16x32_bf16 v[118:121], v[230:233], v[180:183], v[118:121]
	s_waitcnt lgkmcnt(1)
	v_mfma_f32_16x16x32_bf16 v[110:113], v[238:241], v[180:183], v[110:113]
	v_mfma_f32_16x16x32_bf16 v[102:105], v[230:233], v[206:209], v[102:105]
	v_mfma_f32_16x16x32_bf16 v[94:97], v[238:241], v[206:209], v[94:97]
	v_mfma_f32_16x16x32_bf16 v[86:89], v[230:233], v[214:217], v[86:89]
	v_mfma_f32_16x16x32_bf16 v[78:81], v[238:241], v[214:217], v[78:81]
	v_mfma_f32_16x16x32_bf16 v[70:73], v[230:233], v[222:225], v[70:73]
	v_mfma_f32_16x16x32_bf16 v[66:69], v[238:241], v[222:225], v[66:69]
	v_mfma_f32_16x16x32_bf16 v[118:121], v[234:237], v[184:187], v[118:121]
	s_waitcnt lgkmcnt(0)
	v_mfma_f32_16x16x32_bf16 v[110:113], v[242:245], v[184:187], v[110:113]
	v_mfma_f32_16x16x32_bf16 v[102:105], v[234:237], v[210:213], v[102:105]
	v_mfma_f32_16x16x32_bf16 v[94:97], v[242:245], v[210:213], v[94:97]
	v_mfma_f32_16x16x32_bf16 v[86:89], v[234:237], v[218:221], v[86:89]
	v_mfma_f32_16x16x32_bf16 v[78:81], v[242:245], v[218:221], v[78:81]
	v_mfma_f32_16x16x32_bf16 v[70:73], v[234:237], v[226:229], v[70:73]
	v_mfma_f32_16x16x32_bf16 v[66:69], v[242:245], v[226:229], v[66:69]
	s_barrier
	s_mov_b32 m0, s35
	v_lshl_add_u64 v[248:249], s[28:29], 0, v[134:135]
	ds_read_b128 v[180:183], v162 offset:16384
	ds_read_b128 v[184:187], v162 offset:17408
	ds_read_b128 v[206:209], v162 offset:18432
	ds_read_b128 v[210:213], v162 offset:19456
	ds_read_b128 v[214:217], v162 offset:20480
	ds_read_b128 v[218:221], v162 offset:21504
	ds_read_b128 v[222:225], v162 offset:22528
	ds_read_b128 v[226:229], v162 offset:23552
	global_load_lds_dwordx4 v[248:249], off
	s_mov_b32 m0, s36
	v_lshl_add_u64 v[250:251], s[28:29], 0, v[132:133]
	global_load_lds_dwordx4 v[250:251], off
	s_barrier
	s_waitcnt lgkmcnt(7)
	v_mfma_f32_16x16x32_bf16 v[62:65], v[164:167], v[180:183], v[62:65]
	v_mfma_f32_16x16x32_bf16 v[58:61], v[172:175], v[180:183], v[58:61]
	s_waitcnt lgkmcnt(5)
	v_mfma_f32_16x16x32_bf16 v[50:53], v[164:167], v[206:209], v[50:53]
	v_mfma_f32_16x16x32_bf16 v[42:45], v[172:175], v[206:209], v[42:45]
	s_waitcnt lgkmcnt(3)
	v_mfma_f32_16x16x32_bf16 v[34:37], v[164:167], v[214:217], v[34:37]
	v_mfma_f32_16x16x32_bf16 v[26:29], v[172:175], v[214:217], v[26:29]
	s_waitcnt lgkmcnt(1)
	v_mfma_f32_16x16x32_bf16 v[18:21], v[164:167], v[222:225], v[18:21]
	v_mfma_f32_16x16x32_bf16 v[10:13], v[172:175], v[222:225], v[10:13]
	v_mfma_f32_16x16x32_bf16 v[62:65], v[168:171], v[184:187], v[62:65]
	v_mfma_f32_16x16x32_bf16 v[58:61], v[176:179], v[184:187], v[58:61]
	v_mfma_f32_16x16x32_bf16 v[50:53], v[168:171], v[210:213], v[50:53]
	v_mfma_f32_16x16x32_bf16 v[42:45], v[176:179], v[210:213], v[42:45]
	v_mfma_f32_16x16x32_bf16 v[34:37], v[168:171], v[218:221], v[34:37]
	v_mfma_f32_16x16x32_bf16 v[26:29], v[176:179], v[218:221], v[26:29]
	s_waitcnt lgkmcnt(0)
	v_mfma_f32_16x16x32_bf16 v[18:21], v[168:171], v[226:229], v[18:21]
	v_mfma_f32_16x16x32_bf16 v[10:13], v[176:179], v[226:229], v[10:13]
	s_barrier
	s_add_u32 s24, s26, 0xb0000
	s_addc_u32 s25, s27, 0
	s_add_i32 s52, s53, s31
	s_mov_b32 m0, s52
	s_nop 0
	global_load_lds_dwordx4 v0, s[24:25]
	s_add_i32 m0, s52, 0x2000
	s_nop 0
	global_load_lds_dwordx4 v130, s[24:25]
	s_waitcnt vmcnt(6)
	s_barrier
	v_mfma_f32_16x16x32_bf16 v[54:57], v[230:233], v[180:183], v[54:57]
	v_mfma_f32_16x16x32_bf16 v[46:49], v[238:241], v[180:183], v[46:49]
	v_mfma_f32_16x16x32_bf16 v[38:41], v[230:233], v[206:209], v[38:41]
	v_mfma_f32_16x16x32_bf16 v[30:33], v[238:241], v[206:209], v[30:33]
	v_mfma_f32_16x16x32_bf16 v[22:25], v[230:233], v[214:217], v[22:25]
	v_mfma_f32_16x16x32_bf16 v[14:17], v[238:241], v[214:217], v[14:17]
	v_mfma_f32_16x16x32_bf16 v[6:9], v[230:233], v[222:225], v[6:9]
	v_mfma_f32_16x16x32_bf16 v[2:5], v[238:241], v[222:225], v[2:5]
	v_mfma_f32_16x16x32_bf16 v[54:57], v[234:237], v[184:187], v[54:57]
	v_mfma_f32_16x16x32_bf16 v[46:49], v[242:245], v[184:187], v[46:49]
	v_mfma_f32_16x16x32_bf16 v[38:41], v[234:237], v[210:213], v[38:41]
	v_mfma_f32_16x16x32_bf16 v[30:33], v[242:245], v[210:213], v[30:33]
	v_mfma_f32_16x16x32_bf16 v[22:25], v[234:237], v[218:221], v[22:25]
	v_mfma_f32_16x16x32_bf16 v[14:17], v[242:245], v[218:221], v[14:17]
	v_mfma_f32_16x16x32_bf16 v[6:9], v[234:237], v[226:229], v[6:9]
	v_mfma_f32_16x16x32_bf16 v[2:5], v[242:245], v[226:229], v[2:5]
	s_barrier
	s_add_i32 s52, 0, 0x18000
	v_add_u32_e32 v163, s52, v144
	ds_read_b128 v[164:167], v163
	ds_read_b128 v[168:171], v163 offset:1024
	ds_read_b128 v[172:175], v163 offset:2048
	ds_read_b128 v[176:179], v163 offset:3072
	s_add_u32 s24, s28, 0xb0000
	s_addc_u32 s25, s29, 0
	s_mov_b32 m0, s37
	v_lshl_add_u64 v[230:231], s[24:25], 0, v[134:135]
	ds_read_b128 v[180:183], v162 offset:32768
	ds_read_b128 v[184:187], v162 offset:33792
	ds_read_b128 v[206:209], v162 offset:34816
	ds_read_b128 v[210:213], v162 offset:35840
	ds_read_b128 v[214:217], v162 offset:36864
	ds_read_b128 v[218:221], v162 offset:37888
	ds_read_b128 v[222:225], v162 offset:38912
	ds_read_b128 v[226:229], v162 offset:39936
	global_load_lds_dwordx4 v[230:231], off
	s_mov_b32 m0, s42
	s_nop 0
	global_load_lds_dwordx4 v132, s[24:25]
	s_waitcnt lgkmcnt(8)
	s_barrier
	s_waitcnt lgkmcnt(7)
	v_mfma_f32_16x16x32_bf16 v[126:129], v[164:167], v[180:183], v[126:129]
	v_mfma_f32_16x16x32_bf16 v[122:125], v[172:175], v[180:183], v[122:125]
	s_waitcnt lgkmcnt(5)
	v_mfma_f32_16x16x32_bf16 v[114:117], v[164:167], v[206:209], v[114:117]
	v_mfma_f32_16x16x32_bf16 v[106:109], v[172:175], v[206:209], v[106:109]
	s_waitcnt lgkmcnt(3)
	v_mfma_f32_16x16x32_bf16 v[98:101], v[164:167], v[214:217], v[98:101]
	v_mfma_f32_16x16x32_bf16 v[90:93], v[172:175], v[214:217], v[90:93]
	s_waitcnt lgkmcnt(1)
	v_mfma_f32_16x16x32_bf16 v[82:85], v[164:167], v[222:225], v[82:85]
	v_mfma_f32_16x16x32_bf16 v[74:77], v[172:175], v[222:225], v[74:77]
	v_mfma_f32_16x16x32_bf16 v[126:129], v[168:171], v[184:187], v[126:129]
	v_mfma_f32_16x16x32_bf16 v[122:125], v[176:179], v[184:187], v[122:125]
	v_mfma_f32_16x16x32_bf16 v[114:117], v[168:171], v[210:213], v[114:117]
	v_mfma_f32_16x16x32_bf16 v[106:109], v[176:179], v[210:213], v[106:109]
	v_mfma_f32_16x16x32_bf16 v[98:101], v[168:171], v[218:221], v[98:101]
	v_mfma_f32_16x16x32_bf16 v[90:93], v[176:179], v[218:221], v[90:93]
	s_waitcnt lgkmcnt(0)
	v_mfma_f32_16x16x32_bf16 v[82:85], v[168:171], v[226:229], v[82:85]
	v_mfma_f32_16x16x32_bf16 v[74:77], v[176:179], v[226:229], v[74:77]
	s_barrier
	s_add_i32 s28, 0, 0x1c000
	s_add_i32 s24, s52, s31
	v_add_u32_e32 v163, s28, v144
	v_lshl_add_u64 v[140:141], v[140:141], 0, s[94:95]
	s_mov_b32 m0, s24
	ds_read_b128 v[230:233], v163
	ds_read_b128 v[234:237], v163 offset:1024
	ds_read_b128 v[238:241], v163 offset:2048
	ds_read_b128 v[242:245], v163 offset:3072
	global_load_lds_dwordx4 v[140:141], off
	s_add_i32 m0, s24, 0x2000
	v_lshl_add_u64 v[140:141], v[246:247], 0, s[94:95]
	global_load_lds_dwordx4 v[140:141], off
	s_barrier
	s_waitcnt lgkmcnt(3)
	v_mfma_f32_16x16x32_bf16 v[118:121], v[230:233], v[180:183], v[118:121]
	s_waitcnt lgkmcnt(1)
	v_mfma_f32_16x16x32_bf16 v[110:113], v[238:241], v[180:183], v[110:113]
	v_mfma_f32_16x16x32_bf16 v[102:105], v[230:233], v[206:209], v[102:105]
	v_mfma_f32_16x16x32_bf16 v[94:97], v[238:241], v[206:209], v[94:97]
	v_mfma_f32_16x16x32_bf16 v[86:89], v[230:233], v[214:217], v[86:89]
	v_mfma_f32_16x16x32_bf16 v[78:81], v[238:241], v[214:217], v[78:81]
	v_mfma_f32_16x16x32_bf16 v[70:73], v[230:233], v[222:225], v[70:73]
	v_mfma_f32_16x16x32_bf16 v[66:69], v[238:241], v[222:225], v[66:69]
	v_mfma_f32_16x16x32_bf16 v[118:121], v[234:237], v[184:187], v[118:121]
	s_waitcnt lgkmcnt(0)
	v_mfma_f32_16x16x32_bf16 v[110:113], v[242:245], v[184:187], v[110:113]
	v_mfma_f32_16x16x32_bf16 v[102:105], v[234:237], v[210:213], v[102:105]
	v_mfma_f32_16x16x32_bf16 v[94:97], v[242:245], v[210:213], v[94:97]
	v_mfma_f32_16x16x32_bf16 v[86:89], v[234:237], v[218:221], v[86:89]
	v_mfma_f32_16x16x32_bf16 v[78:81], v[242:245], v[218:221], v[78:81]
	v_mfma_f32_16x16x32_bf16 v[70:73], v[234:237], v[226:229], v[70:73]
	v_mfma_f32_16x16x32_bf16 v[66:69], v[242:245], v[226:229], v[66:69]
	s_barrier
	s_mov_b32 m0, s44
	v_lshl_add_u64 v[140:141], v[248:249], 0, s[94:95]
	ds_read_b128 v[180:183], v162 offset:49152
	ds_read_b128 v[184:187], v162 offset:50176
	ds_read_b128 v[206:209], v162 offset:51200
	ds_read_b128 v[210:213], v162 offset:52224
	ds_read_b128 v[214:217], v162 offset:53248
	ds_read_b128 v[218:221], v162 offset:54272
	ds_read_b128 v[222:225], v162 offset:55296
	ds_read_b128 v[226:229], v162 offset:56320
	global_load_lds_dwordx4 v[140:141], off
	s_mov_b32 m0, s45
	v_lshl_add_u64 v[140:141], v[250:251], 0, s[94:95]
	global_load_lds_dwordx4 v[140:141], off
	s_barrier
	s_waitcnt lgkmcnt(7)
	v_mfma_f32_16x16x32_bf16 v[62:65], v[164:167], v[180:183], v[62:65]
	v_mfma_f32_16x16x32_bf16 v[58:61], v[172:175], v[180:183], v[58:61]
	s_waitcnt lgkmcnt(5)
	v_mfma_f32_16x16x32_bf16 v[50:53], v[164:167], v[206:209], v[50:53]
	v_mfma_f32_16x16x32_bf16 v[42:45], v[172:175], v[206:209], v[42:45]
	s_waitcnt lgkmcnt(3)
	v_mfma_f32_16x16x32_bf16 v[34:37], v[164:167], v[214:217], v[34:37]
	v_mfma_f32_16x16x32_bf16 v[26:29], v[172:175], v[214:217], v[26:29]
	s_waitcnt lgkmcnt(1)
	v_mfma_f32_16x16x32_bf16 v[18:21], v[164:167], v[222:225], v[18:21]
	v_mfma_f32_16x16x32_bf16 v[10:13], v[172:175], v[222:225], v[10:13]
	v_mfma_f32_16x16x32_bf16 v[62:65], v[168:171], v[184:187], v[62:65]
	v_mfma_f32_16x16x32_bf16 v[58:61], v[176:179], v[184:187], v[58:61]
	v_mfma_f32_16x16x32_bf16 v[50:53], v[168:171], v[210:213], v[50:53]
	v_mfma_f32_16x16x32_bf16 v[42:45], v[176:179], v[210:213], v[42:45]
	v_mfma_f32_16x16x32_bf16 v[34:37], v[168:171], v[218:221], v[34:37]
	v_mfma_f32_16x16x32_bf16 v[26:29], v[176:179], v[218:221], v[26:29]
	s_waitcnt lgkmcnt(0)
	v_mfma_f32_16x16x32_bf16 v[18:21], v[168:171], v[226:229], v[18:21]
	v_mfma_f32_16x16x32_bf16 v[10:13], v[176:179], v[226:229], v[10:13]
	s_barrier
	s_add_u32 s24, s26, 0xb0080
	s_addc_u32 s25, s27, 0
	s_add_i32 s26, s28, s31
	s_mov_b32 m0, s26
	s_nop 0
	global_load_lds_dwordx4 v0, s[24:25]
	s_add_i32 m0, s26, 0x2000
	s_nop 0
	global_load_lds_dwordx4 v130, s[24:25]
	s_waitcnt vmcnt(6)
	s_barrier
	v_mfma_f32_16x16x32_bf16 v[54:57], v[230:233], v[180:183], v[54:57]
	v_mfma_f32_16x16x32_bf16 v[46:49], v[238:241], v[180:183], v[46:49]
	v_mfma_f32_16x16x32_bf16 v[38:41], v[230:233], v[206:209], v[38:41]
	v_mfma_f32_16x16x32_bf16 v[30:33], v[238:241], v[206:209], v[30:33]
	v_mfma_f32_16x16x32_bf16 v[22:25], v[230:233], v[214:217], v[22:25]
	v_mfma_f32_16x16x32_bf16 v[14:17], v[238:241], v[214:217], v[14:17]
	v_mfma_f32_16x16x32_bf16 v[6:9], v[230:233], v[222:225], v[6:9]
	v_mfma_f32_16x16x32_bf16 v[2:5], v[238:241], v[222:225], v[2:5]
	v_mfma_f32_16x16x32_bf16 v[54:57], v[234:237], v[184:187], v[54:57]
	v_mfma_f32_16x16x32_bf16 v[46:49], v[242:245], v[184:187], v[46:49]
	v_mfma_f32_16x16x32_bf16 v[38:41], v[234:237], v[210:213], v[38:41]
	v_mfma_f32_16x16x32_bf16 v[30:33], v[242:245], v[210:213], v[30:33]
	v_mfma_f32_16x16x32_bf16 v[22:25], v[234:237], v[218:221], v[22:25]
	v_mfma_f32_16x16x32_bf16 v[14:17], v[242:245], v[218:221], v[14:17]
	v_mfma_f32_16x16x32_bf16 v[6:9], v[234:237], v[226:229], v[6:9]
	v_mfma_f32_16x16x32_bf16 v[2:5], v[242:245], v[226:229], v[2:5]
	s_barrier
	s_add_i32 s51, s51, 2
	s_add_u32 s40, s40, 0x100
	s_addc_u32 s41, s41, 0
	s_cmp_gt_u32 s51, 41
	s_mov_b64 s[24:25], s[22:23]
	s_cbranch_scc0 .LBB0_331
	v_lshl_or_b32 v140, s50, 8, v145
	v_lshl_add_u32 v164, s49, 8, v143
	v_ashrrev_i32_e32 v141, 31, v140
	v_ashrrev_i32_e32 v165, 31, v164
	v_lshl_add_u64 v[166:167], v[140:141], 1, s[20:21]
	v_lshlrev_b64 v[140:141], 11, v[164:165]
	v_lshl_add_u64 v[140:141], v[166:167], 0, v[140:141]
	v_pk_add_f32 v[128:129], v[128:129], 0 op_sel_hi:[1,0]
	v_pk_add_f32 v[126:127], v[126:127], 0 op_sel_hi:[1,0]
	v_pk_add_f32 v[168:169], v[124:125], 0 op_sel_hi:[1,0]
	v_pk_add_f32 v[124:125], v[122:123], 0 op_sel_hi:[1,0]
	v_cvt_pk_bf16_f32 v122, v126, v127
	v_cvt_pk_bf16_f32 v123, v128, v129
	v_pk_add_f32 v[118:119], v[118:119], 0 op_sel_hi:[1,0]
	v_cvt_pk_bf16_f32 v124, v124, v125
	v_cvt_pk_bf16_f32 v125, v168, v169
	global_store_dwordx4 v[140:141], v[122:125], off
	v_pk_add_f32 v[120:121], v[120:121], 0 op_sel_hi:[1,0]
	v_pk_add_f32 v[114:115], v[114:115], 0 op_sel_hi:[1,0]
	v_pk_add_f32 v[122:123], v[112:113], 0 op_sel_hi:[1,0]
	v_pk_add_f32 v[112:113], v[110:111], 0 op_sel_hi:[1,0]
	v_cvt_pk_bf16_f32 v110, v118, v119
	v_cvt_pk_bf16_f32 v111, v120, v121
	v_pk_add_f32 v[102:103], v[102:103], 0 op_sel_hi:[1,0]
	v_cvt_pk_bf16_f32 v112, v112, v113
	v_cvt_pk_bf16_f32 v113, v122, v123
	global_store_dwordx4 v[140:141], v[110:113], off offset:256
	v_pk_add_f32 v[104:105], v[104:105], 0 op_sel_hi:[1,0]
	v_pk_add_f32 v[98:99], v[98:99], 0 op_sel_hi:[1,0]
	v_or_b32_e32 v110, 16, v164
	v_ashrrev_i32_e32 v111, 31, v110
	v_lshlrev_b64 v[110:111], 11, v[110:111]
	v_lshl_add_u64 v[110:111], v[166:167], 0, v[110:111]
	v_pk_add_f32 v[112:113], v[116:117], 0 op_sel_hi:[1,0]
	v_pk_add_f32 v[116:117], v[108:109], 0 op_sel_hi:[1,0]
	v_pk_add_f32 v[108:109], v[106:107], 0 op_sel_hi:[1,0]
	v_cvt_pk_bf16_f32 v106, v114, v115
	v_cvt_pk_bf16_f32 v107, v112, v113
	v_pk_add_f32 v[86:87], v[86:87], 0 op_sel_hi:[1,0]
	v_cvt_pk_bf16_f32 v108, v108, v109
	v_cvt_pk_bf16_f32 v109, v116, v117
	global_store_dwordx4 v[110:111], v[106:109], off
	v_pk_add_f32 v[88:89], v[88:89], 0 op_sel_hi:[1,0]
	v_pk_add_f32 v[82:83], v[82:83], 0 op_sel_hi:[1,0]
	v_pk_add_f32 v[106:107], v[96:97], 0 op_sel_hi:[1,0]
	v_pk_add_f32 v[96:97], v[94:95], 0 op_sel_hi:[1,0]
	v_cvt_pk_bf16_f32 v94, v102, v103
	v_cvt_pk_bf16_f32 v95, v104, v105
	v_pk_add_f32 v[72:73], v[72:73], 0 op_sel_hi:[1,0]
	v_cvt_pk_bf16_f32 v96, v96, v97
	v_cvt_pk_bf16_f32 v97, v106, v107
	global_store_dwordx4 v[110:111], v[94:97], off offset:256
	v_pk_add_f32 v[70:71], v[70:71], 0 op_sel_hi:[1,0]
	v_pk_add_f32 v[62:63], v[62:63], 0 op_sel_hi:[1,0]
	v_or_b32_e32 v94, 32, v164
	v_ashrrev_i32_e32 v95, 31, v94
	v_lshlrev_b64 v[94:95], 11, v[94:95]
	v_lshl_add_u64 v[94:95], v[166:167], 0, v[94:95]
	v_pk_add_f32 v[96:97], v[100:101], 0 op_sel_hi:[1,0]
	v_pk_add_f32 v[100:101], v[92:93], 0 op_sel_hi:[1,0]
	v_pk_add_f32 v[92:93], v[90:91], 0 op_sel_hi:[1,0]
	v_cvt_pk_bf16_f32 v90, v98, v99
	v_cvt_pk_bf16_f32 v91, v96, v97
	v_pk_add_f32 v[64:65], v[64:65], 0 op_sel_hi:[1,0]
	v_cvt_pk_bf16_f32 v92, v92, v93
	v_cvt_pk_bf16_f32 v93, v100, v101
	global_store_dwordx4 v[94:95], v[90:93], off
	s_mov_b64 s[22:23], 0x40000
	v_pk_add_f32 v[56:57], v[56:57], 0 op_sel_hi:[1,0]
	v_pk_add_f32 v[90:91], v[80:81], 0 op_sel_hi:[1,0]
	v_pk_add_f32 v[80:81], v[78:79], 0 op_sel_hi:[1,0]
	v_cvt_pk_bf16_f32 v78, v86, v87
	v_cvt_pk_bf16_f32 v79, v88, v89
	v_pk_add_f32 v[54:55], v[54:55], 0 op_sel_hi:[1,0]
	v_cvt_pk_bf16_f32 v80, v80, v81
	v_cvt_pk_bf16_f32 v81, v90, v91
	global_store_dwordx4 v[94:95], v[78:81], off offset:256
	v_pk_add_f32 v[50:51], v[50:51], 0 op_sel_hi:[1,0]
	v_pk_add_f32 v[40:41], v[40:41], 0 op_sel_hi:[1,0]
	v_or_b32_e32 v78, 48, v164
	v_ashrrev_i32_e32 v79, 31, v78
	v_lshlrev_b64 v[78:79], 11, v[78:79]
	v_lshl_add_u64 v[78:79], v[166:167], 0, v[78:79]
	v_pk_add_f32 v[80:81], v[84:85], 0 op_sel_hi:[1,0]
	v_pk_add_f32 v[84:85], v[76:77], 0 op_sel_hi:[1,0]
	v_pk_add_f32 v[76:77], v[74:75], 0 op_sel_hi:[1,0]
	v_cvt_pk_bf16_f32 v74, v82, v83
	v_cvt_pk_bf16_f32 v75, v80, v81
	v_pk_add_f32 v[38:39], v[38:39], 0 op_sel_hi:[1,0]
	v_cvt_pk_bf16_f32 v76, v76, v77
	v_cvt_pk_bf16_f32 v77, v84, v85
	global_store_dwordx4 v[78:79], v[74:77], off
	v_pk_add_f32 v[34:35], v[34:35], 0 op_sel_hi:[1,0]
	v_pk_add_f32 v[24:25], v[24:25], 0 op_sel_hi:[1,0]
	v_pk_add_f32 v[74:75], v[68:69], 0 op_sel_hi:[1,0]
	v_pk_add_f32 v[68:69], v[66:67], 0 op_sel_hi:[1,0]
	v_cvt_pk_bf16_f32 v66, v70, v71
	v_cvt_pk_bf16_f32 v67, v72, v73
	v_pk_add_f32 v[22:23], v[22:23], 0 op_sel_hi:[1,0]
	v_cvt_pk_bf16_f32 v68, v68, v69
	v_cvt_pk_bf16_f32 v69, v74, v75
	global_store_dwordx4 v[78:79], v[66:69], off offset:256
	v_pk_add_f32 v[18:19], v[18:19], 0 op_sel_hi:[1,0]
	s_mov_b32 s50, s47
	v_pk_add_f32 v[68:69], v[60:61], 0 op_sel_hi:[1,0]
	v_pk_add_f32 v[60:61], v[58:59], 0 op_sel_hi:[1,0]
	v_cvt_pk_bf16_f32 v58, v62, v63
	v_add_co_u32_e32 v62, vcc, s67, v140
	v_cvt_pk_bf16_f32 v59, v64, v65
	v_cvt_pk_bf16_f32 v60, v60, v61
	v_cvt_pk_bf16_f32 v61, v68, v69
	v_lshl_add_u64 v[66:67], v[140:141], 0, s[22:23]
	s_nop 0
	v_addc_co_u32_e32 v63, vcc, 0, v141, vcc
	global_store_dwordx4 v[62:63], v[58:61], off
	s_mov_b64 s[22:23], 0x48000
	s_mov_b32 s49, s48
	v_pk_add_f32 v[58:59], v[48:49], 0 op_sel_hi:[1,0]
	v_pk_add_f32 v[48:49], v[46:47], 0 op_sel_hi:[1,0]
	v_cvt_pk_bf16_f32 v46, v54, v55
	v_cvt_pk_bf16_f32 v47, v56, v57
	s_mov_b64 s[24:25], s[2:3]
	v_cvt_pk_bf16_f32 v48, v48, v49
	v_cvt_pk_bf16_f32 v49, v58, v59
	global_store_dwordx4 v[66:67], v[46:49], off offset:256
	v_pk_add_f32 v[8:9], v[8:9], 0 op_sel_hi:[1,0]
	v_pk_add_f32 v[6:7], v[6:7], 0 op_sel_hi:[1,0]
	v_pk_add_f32 v[48:49], v[52:53], 0 op_sel_hi:[1,0]
	v_pk_add_f32 v[52:53], v[44:45], 0 op_sel_hi:[1,0]
	v_pk_add_f32 v[44:45], v[42:43], 0 op_sel_hi:[1,0]
	v_cvt_pk_bf16_f32 v42, v50, v51
	v_cvt_pk_bf16_f32 v43, v48, v49
	v_add_co_u32_e32 v48, vcc, s68, v140
	v_cvt_pk_bf16_f32 v44, v44, v45
	v_cvt_pk_bf16_f32 v45, v52, v53
	v_lshl_add_u64 v[46:47], v[140:141], 0, s[22:23]
	s_nop 0
	v_addc_co_u32_e32 v49, vcc, 0, v141, vcc
	global_store_dwordx4 v[48:49], v[42:45], off
	s_mov_b64 s[22:23], 0x50000
	s_nop 0
	v_pk_add_f32 v[42:43], v[32:33], 0 op_sel_hi:[1,0]
	v_pk_add_f32 v[32:33], v[30:31], 0 op_sel_hi:[1,0]
	v_cvt_pk_bf16_f32 v30, v38, v39
	v_cvt_pk_bf16_f32 v31, v40, v41
	s_nop 0
	v_cvt_pk_bf16_f32 v32, v32, v33
	v_cvt_pk_bf16_f32 v33, v42, v43
	global_store_dwordx4 v[46:47], v[30:33], off offset:256
	s_nop 1
	v_lshl_add_u64 v[30:31], v[140:141], 0, s[22:23]
	v_pk_add_f32 v[32:33], v[36:37], 0 op_sel_hi:[1,0]
	s_mov_b32 s22, 0x50000
	v_pk_add_f32 v[36:37], v[28:29], 0 op_sel_hi:[1,0]
	v_pk_add_f32 v[28:29], v[26:27], 0 op_sel_hi:[1,0]
	v_cvt_pk_bf16_f32 v26, v34, v35
	v_cvt_pk_bf16_f32 v27, v32, v33
	v_add_co_u32_e32 v32, vcc, s22, v140
	v_cvt_pk_bf16_f32 v28, v28, v29
	v_cvt_pk_bf16_f32 v29, v36, v37
	s_mov_b64 s[22:23], 0x58000
	s_nop 0
	v_addc_co_u32_e32 v33, vcc, 0, v141, vcc
	global_store_dwordx4 v[32:33], v[26:29], off
	s_nop 1
	v_pk_add_f32 v[26:27], v[16:17], 0 op_sel_hi:[1,0]
	v_pk_add_f32 v[16:17], v[14:15], 0 op_sel_hi:[1,0]
	v_cvt_pk_bf16_f32 v14, v22, v23
	v_cvt_pk_bf16_f32 v15, v24, v25
	s_nop 0
	v_cvt_pk_bf16_f32 v16, v16, v17
	v_cvt_pk_bf16_f32 v17, v26, v27
	global_store_dwordx4 v[30:31], v[14:17], off offset:256
	s_nop 1
	v_lshl_add_u64 v[14:15], v[140:141], 0, s[22:23]
	v_pk_add_f32 v[16:17], v[20:21], 0 op_sel_hi:[1,0]
	s_mov_b32 s22, 0x58000
	v_pk_add_f32 v[20:21], v[12:13], 0 op_sel_hi:[1,0]
	v_pk_add_f32 v[12:13], v[10:11], 0 op_sel_hi:[1,0]
	v_cvt_pk_bf16_f32 v10, v18, v19
	v_cvt_pk_bf16_f32 v11, v16, v17
	v_add_co_u32_e32 v16, vcc, s22, v140
	v_cvt_pk_bf16_f32 v12, v12, v13
	v_cvt_pk_bf16_f32 v13, v20, v21
	s_mov_b64 s[22:23], s[0:1]
	s_nop 0
	v_addc_co_u32_e32 v17, vcc, 0, v141, vcc
	global_store_dwordx4 v[16:17], v[10:13], off
	s_and_b64 vcc, exec, s[38:39]
	s_nop 0
	v_pk_add_f32 v[10:11], v[4:5], 0 op_sel_hi:[1,0]
	v_pk_add_f32 v[4:5], v[2:3], 0 op_sel_hi:[1,0]
	v_cvt_pk_bf16_f32 v2, v6, v7
	v_cvt_pk_bf16_f32 v3, v8, v9
	s_nop 0
	v_cvt_pk_bf16_f32 v4, v4, v5
	v_cvt_pk_bf16_f32 v5, v10, v11
	global_store_dwordx4 v[14:15], v[2:5], off offset:256
	s_cbranch_vccz .LBB0_320
	s_waitcnt vmcnt(16)
	s_cmpk_gt_u32 s30, 0xff
	s_cbranch_scc1 .LBB0_335
	s_barrier

.Lkprio_1:
.LBB0_360:
	s_add_u32 s44, s42, 0xfffc0080
	s_addc_u32 s45, s43, -1
	s_add_i32 s63, 0, 0x10000
	v_add_u32_e32 v0, s63, v206
	ds_read_b128 v[82:85], v0
	ds_read_b128 v[86:89], v0 offset:1024
	ds_read_b128 v[90:93], v0 offset:2048
	ds_read_b128 v[94:97], v0 offset:3072
	s_cmp_eq_u32 s62, 12
	s_cselect_b32 s47, s1, s45
	s_cselect_b32 s46, s3, s44
	s_cselect_b32 s45, s31, s61
	s_cselect_b32 s44, s35, s60
	v_lshl_add_u64 v[230:231], s[42:43], 0, v[174:175]
	s_add_i32 m0, s51, 0xc000
	ds_read_b128 v[176:179], v208
	ds_read_b128 v[180:183], v208 offset:1024
	ds_read_b128 v[184:187], v208 offset:2048
	ds_read_b128 v[210:213], v208 offset:3072
	ds_read_b128 v[214:217], v208 offset:4096
	ds_read_b128 v[218:221], v208 offset:5120
	ds_read_b128 v[222:225], v208 offset:6144
	ds_read_b128 v[226:229], v208 offset:7168
	global_load_lds_dwordx4 v[230:231], off
	s_add_i32 m0, s51, 0xe000
	s_nop 0
	global_load_lds_dwordx4 v172, s[42:43]
	s_waitcnt lgkmcnt(8)
	s_barrier
	s_waitcnt lgkmcnt(7)
	v_mfma_f32_16x16x32_bf16 v[142:145], v[82:85], v[176:179], v[142:145]
	v_mfma_f32_16x16x32_bf16 v[138:141], v[90:93], v[176:179], v[138:141]
	s_waitcnt lgkmcnt(5)
	v_mfma_f32_16x16x32_bf16 v[126:129], v[82:85], v[184:187], v[126:129]
	v_mfma_f32_16x16x32_bf16 v[122:125], v[90:93], v[184:187], v[122:125]
	s_waitcnt lgkmcnt(3)
	v_mfma_f32_16x16x32_bf16 v[110:113], v[82:85], v[214:217], v[110:113]
	v_mfma_f32_16x16x32_bf16 v[106:109], v[90:93], v[214:217], v[106:109]
	s_waitcnt lgkmcnt(1)
	v_mfma_f32_16x16x32_bf16 v[78:81], v[82:85], v[222:225], v[78:81]
	v_mfma_f32_16x16x32_bf16 v[74:77], v[90:93], v[222:225], v[74:77]
	v_mfma_f32_16x16x32_bf16 v[142:145], v[86:89], v[180:183], v[142:145]
	v_mfma_f32_16x16x32_bf16 v[138:141], v[94:97], v[180:183], v[138:141]
	v_mfma_f32_16x16x32_bf16 v[126:129], v[86:89], v[210:213], v[126:129]
	v_mfma_f32_16x16x32_bf16 v[122:125], v[94:97], v[210:213], v[122:125]
	v_mfma_f32_16x16x32_bf16 v[110:113], v[86:89], v[218:221], v[110:113]
	v_mfma_f32_16x16x32_bf16 v[106:109], v[94:97], v[218:221], v[106:109]
	s_waitcnt lgkmcnt(0)
	v_mfma_f32_16x16x32_bf16 v[78:81], v[86:89], v[226:229], v[78:81]
	v_mfma_f32_16x16x32_bf16 v[74:77], v[94:97], v[226:229], v[74:77]
	s_barrier
	s_add_i32 s66, 0, 0x14000
	s_add_i32 s63, s63, s50
	v_add_u32_e32 v0, s66, v206
	v_lshl_add_u64 v[246:247], s[44:45], 0, v[164:165]
	s_mov_b32 m0, s63
	ds_read_b128 v[230:233], v0
	ds_read_b128 v[234:237], v0 offset:1024
	ds_read_b128 v[238:241], v0 offset:2048
	ds_read_b128 v[242:245], v0 offset:3072
	global_load_lds_dwordx4 v[246:247], off
	s_add_i32 m0, s63, 0x2000
	v_lshl_add_u64 v[248:249], s[44:45], 0, v[168:169]
	global_load_lds_dwordx4 v[248:249], off
	s_barrier
	s_waitcnt lgkmcnt(3)
	v_mfma_f32_16x16x32_bf16 v[134:137], v[230:233], v[176:179], v[134:137]
	s_waitcnt lgkmcnt(1)
	v_mfma_f32_16x16x32_bf16 v[130:133], v[238:241], v[176:179], v[130:133]
	v_mfma_f32_16x16x32_bf16 v[118:121], v[230:233], v[184:187], v[118:121]
	v_mfma_f32_16x16x32_bf16 v[114:117], v[238:241], v[184:187], v[114:117]
	v_mfma_f32_16x16x32_bf16 v[102:105], v[230:233], v[214:217], v[102:105]
	v_mfma_f32_16x16x32_bf16 v[98:101], v[238:241], v[214:217], v[98:101]
	v_mfma_f32_16x16x32_bf16 v[70:73], v[230:233], v[222:225], v[70:73]
	v_mfma_f32_16x16x32_bf16 v[66:69], v[238:241], v[222:225], v[66:69]
	v_mfma_f32_16x16x32_bf16 v[134:137], v[234:237], v[180:183], v[134:137]
	s_waitcnt lgkmcnt(0)
	v_mfma_f32_16x16x32_bf16 v[130:133], v[242:245], v[180:183], v[130:133]
	v_mfma_f32_16x16x32_bf16 v[118:121], v[234:237], v[210:213], v[118:121]
	v_mfma_f32_16x16x32_bf16 v[114:117], v[242:245], v[210:213], v[114:117]
	v_mfma_f32_16x16x32_bf16 v[102:105], v[234:237], v[218:221], v[102:105]
	v_mfma_f32_16x16x32_bf16 v[98:101], v[242:245], v[218:221], v[98:101]
	v_mfma_f32_16x16x32_bf16 v[70:73], v[234:237], v[226:229], v[70:73]
	v_mfma_f32_16x16x32_bf16 v[66:69], v[242:245], v[226:229], v[66:69]
	s_barrier
	s_mov_b32 m0, s51
	v_lshl_add_u64 v[250:251], s[46:47], 0, v[162:163]
	ds_read_b128 v[176:179], v208 offset:16384
	ds_read_b128 v[180:183], v208 offset:17408
	ds_read_b128 v[184:187], v208 offset:18432
	ds_read_b128 v[210:213], v208 offset:19456
	ds_read_b128 v[214:217], v208 offset:20480
	ds_read_b128 v[218:221], v208 offset:21504
	ds_read_b128 v[222:225], v208 offset:22528
	ds_read_b128 v[226:229], v208 offset:23552
	global_load_lds_dwordx4 v[250:251], off
	s_mov_b32 m0, s52
	v_lshl_add_u64 v[252:253], s[46:47], 0, v[166:167]
	global_load_lds_dwordx4 v[252:253], off
	s_barrier
	s_waitcnt lgkmcnt(7)
	v_mfma_f32_16x16x32_bf16 v[62:65], v[82:85], v[176:179], v[62:65]
	v_mfma_f32_16x16x32_bf16 v[58:61], v[90:93], v[176:179], v[58:61]
	s_waitcnt lgkmcnt(5)
	v_mfma_f32_16x16x32_bf16 v[46:49], v[82:85], v[184:187], v[46:49]
	v_mfma_f32_16x16x32_bf16 v[42:45], v[90:93], v[184:187], v[42:45]
	s_waitcnt lgkmcnt(3)
	v_mfma_f32_16x16x32_bf16 v[30:33], v[82:85], v[214:217], v[30:33]
	v_mfma_f32_16x16x32_bf16 v[26:29], v[90:93], v[214:217], v[26:29]
	s_waitcnt lgkmcnt(1)
	v_mfma_f32_16x16x32_bf16 v[14:17], v[82:85], v[222:225], v[14:17]
	v_mfma_f32_16x16x32_bf16 v[10:13], v[90:93], v[222:225], v[10:13]
	v_mfma_f32_16x16x32_bf16 v[62:65], v[86:89], v[180:183], v[62:65]
	v_mfma_f32_16x16x32_bf16 v[58:61], v[94:97], v[180:183], v[58:61]
	v_mfma_f32_16x16x32_bf16 v[46:49], v[86:89], v[210:213], v[46:49]
	v_mfma_f32_16x16x32_bf16 v[42:45], v[94:97], v[210:213], v[42:45]
	v_mfma_f32_16x16x32_bf16 v[30:33], v[86:89], v[218:221], v[30:33]
	v_mfma_f32_16x16x32_bf16 v[26:29], v[94:97], v[218:221], v[26:29]
	s_waitcnt lgkmcnt(0)
	v_mfma_f32_16x16x32_bf16 v[14:17], v[86:89], v[226:229], v[14:17]
	v_mfma_f32_16x16x32_bf16 v[10:13], v[94:97], v[226:229], v[10:13]
	s_barrier
	s_add_u32 s64, s44, 0x40000
	s_addc_u32 s65, s45, 0
	s_add_i32 s63, s66, s50
	s_mov_b32 m0, s63
	s_nop 0
	global_load_lds_dwordx4 v164, s[64:65]
	s_add_i32 m0, s63, 0x2000
	s_nop 0
	global_load_lds_dwordx4 v168, s[64:65]
	s_waitcnt vmcnt(6)
	s_barrier
	v_mfma_f32_16x16x32_bf16 v[54:57], v[230:233], v[176:179], v[54:57]
	v_mfma_f32_16x16x32_bf16 v[50:53], v[238:241], v[176:179], v[50:53]
	v_mfma_f32_16x16x32_bf16 v[38:41], v[230:233], v[184:187], v[38:41]
	v_mfma_f32_16x16x32_bf16 v[34:37], v[238:241], v[184:187], v[34:37]
	v_mfma_f32_16x16x32_bf16 v[22:25], v[230:233], v[214:217], v[22:25]
	v_mfma_f32_16x16x32_bf16 v[18:21], v[238:241], v[214:217], v[18:21]
	v_mfma_f32_16x16x32_bf16 v[6:9], v[230:233], v[222:225], v[6:9]
	v_mfma_f32_16x16x32_bf16 v[2:5], v[238:241], v[222:225], v[2:5]
	v_mfma_f32_16x16x32_bf16 v[54:57], v[234:237], v[180:183], v[54:57]
	v_mfma_f32_16x16x32_bf16 v[50:53], v[242:245], v[180:183], v[50:53]
	v_mfma_f32_16x16x32_bf16 v[38:41], v[234:237], v[210:213], v[38:41]
	v_mfma_f32_16x16x32_bf16 v[34:37], v[242:245], v[210:213], v[34:37]
	v_mfma_f32_16x16x32_bf16 v[22:25], v[234:237], v[218:221], v[22:25]
	v_mfma_f32_16x16x32_bf16 v[18:21], v[242:245], v[218:221], v[18:21]
	v_mfma_f32_16x16x32_bf16 v[6:9], v[234:237], v[226:229], v[6:9]
	v_mfma_f32_16x16x32_bf16 v[2:5], v[242:245], v[226:229], v[2:5]
	s_barrier
	s_add_i32 s63, 0, 0x18000
	v_add_u32_e32 v0, s63, v206
	ds_read_b128 v[82:85], v0
	ds_read_b128 v[86:89], v0 offset:1024
	ds_read_b128 v[90:93], v0 offset:2048
	ds_read_b128 v[94:97], v0 offset:3072
	s_add_u32 s46, s46, 0x40000
	s_addc_u32 s47, s47, 0
	s_mov_b32 m0, s53
	v_lshl_add_u64 v[230:231], s[46:47], 0, v[162:163]
	ds_read_b128 v[176:179], v208 offset:32768
	ds_read_b128 v[180:183], v208 offset:33792
	ds_read_b128 v[184:187], v208 offset:34816
	ds_read_b128 v[210:213], v208 offset:35840
	ds_read_b128 v[214:217], v208 offset:36864
	ds_read_b128 v[218:221], v208 offset:37888
	ds_read_b128 v[222:225], v208 offset:38912
	ds_read_b128 v[226:229], v208 offset:39936
	global_load_lds_dwordx4 v[230:231], off
	s_mov_b32 m0, s54
	s_nop 0
	global_load_lds_dwordx4 v166, s[46:47]
	s_waitcnt lgkmcnt(8)
	s_barrier
	s_waitcnt lgkmcnt(7)
	v_mfma_f32_16x16x32_bf16 v[142:145], v[82:85], v[176:179], v[142:145]
	v_mfma_f32_16x16x32_bf16 v[138:141], v[90:93], v[176:179], v[138:141]
	s_waitcnt lgkmcnt(5)
	v_mfma_f32_16x16x32_bf16 v[126:129], v[82:85], v[184:187], v[126:129]
	v_mfma_f32_16x16x32_bf16 v[122:125], v[90:93], v[184:187], v[122:125]
	s_waitcnt lgkmcnt(3)
	v_mfma_f32_16x16x32_bf16 v[110:113], v[82:85], v[214:217], v[110:113]
	v_mfma_f32_16x16x32_bf16 v[106:109], v[90:93], v[214:217], v[106:109]
	s_waitcnt lgkmcnt(1)
	v_mfma_f32_16x16x32_bf16 v[78:81], v[82:85], v[222:225], v[78:81]
	v_mfma_f32_16x16x32_bf16 v[74:77], v[90:93], v[222:225], v[74:77]
	v_mfma_f32_16x16x32_bf16 v[142:145], v[86:89], v[180:183], v[142:145]
	v_mfma_f32_16x16x32_bf16 v[138:141], v[94:97], v[180:183], v[138:141]
	v_mfma_f32_16x16x32_bf16 v[126:129], v[86:89], v[210:213], v[126:129]
	v_mfma_f32_16x16x32_bf16 v[122:125], v[94:97], v[210:213], v[122:125]
	v_mfma_f32_16x16x32_bf16 v[110:113], v[86:89], v[218:221], v[110:113]
	v_mfma_f32_16x16x32_bf16 v[106:109], v[94:97], v[218:221], v[106:109]
	s_waitcnt lgkmcnt(0)
	v_mfma_f32_16x16x32_bf16 v[78:81], v[86:89], v[226:229], v[78:81]
	v_mfma_f32_16x16x32_bf16 v[74:77], v[94:97], v[226:229], v[74:77]
	s_barrier
	s_add_i32 s46, 0, 0x1c000
	s_add_i32 s47, s63, s50
	v_add_u32_e32 v0, s46, v206
	v_lshl_add_u64 v[246:247], v[246:247], 0, s[94:95]
	s_mov_b32 m0, s47
	ds_read_b128 v[230:233], v0
	ds_read_b128 v[234:237], v0 offset:1024
	ds_read_b128 v[238:241], v0 offset:2048
	ds_read_b128 v[242:245], v0 offset:3072
	global_load_lds_dwordx4 v[246:247], off
	s_add_i32 m0, s47, 0x2000
	v_lshl_add_u64 v[246:247], v[248:249], 0, s[94:95]
	global_load_lds_dwordx4 v[246:247], off
	s_barrier
	s_waitcnt lgkmcnt(3)
	v_mfma_f32_16x16x32_bf16 v[134:137], v[230:233], v[176:179], v[134:137]
	s_waitcnt lgkmcnt(1)
	v_mfma_f32_16x16x32_bf16 v[130:133], v[238:241], v[176:179], v[130:133]
	v_mfma_f32_16x16x32_bf16 v[118:121], v[230:233], v[184:187], v[118:121]
	v_mfma_f32_16x16x32_bf16 v[114:117], v[238:241], v[184:187], v[114:117]
	v_mfma_f32_16x16x32_bf16 v[102:105], v[230:233], v[214:217], v[102:105]
	v_mfma_f32_16x16x32_bf16 v[98:101], v[238:241], v[214:217], v[98:101]
	v_mfma_f32_16x16x32_bf16 v[70:73], v[230:233], v[222:225], v[70:73]
	v_mfma_f32_16x16x32_bf16 v[66:69], v[238:241], v[222:225], v[66:69]
	v_mfma_f32_16x16x32_bf16 v[134:137], v[234:237], v[180:183], v[134:137]
	s_waitcnt lgkmcnt(0)
	v_mfma_f32_16x16x32_bf16 v[130:133], v[242:245], v[180:183], v[130:133]
	v_mfma_f32_16x16x32_bf16 v[118:121], v[234:237], v[210:213], v[118:121]
	v_mfma_f32_16x16x32_bf16 v[114:117], v[242:245], v[210:213], v[114:117]
	v_mfma_f32_16x16x32_bf16 v[102:105], v[234:237], v[218:221], v[102:105]
	v_mfma_f32_16x16x32_bf16 v[98:101], v[242:245], v[218:221], v[98:101]
	v_mfma_f32_16x16x32_bf16 v[70:73], v[234:237], v[226:229], v[70:73]
	v_mfma_f32_16x16x32_bf16 v[66:69], v[242:245], v[226:229], v[66:69]
	s_barrier
	s_mov_b32 m0, s56
	v_lshl_add_u64 v[246:247], v[250:251], 0, s[94:95]
	ds_read_b128 v[176:179], v208 offset:49152
	ds_read_b128 v[180:183], v208 offset:50176
	ds_read_b128 v[184:187], v208 offset:51200
	ds_read_b128 v[210:213], v208 offset:52224
	ds_read_b128 v[214:217], v208 offset:53248
	ds_read_b128 v[218:221], v208 offset:54272
	ds_read_b128 v[222:225], v208 offset:55296
	ds_read_b128 v[226:229], v208 offset:56320
	global_load_lds_dwordx4 v[246:247], off
	s_mov_b32 m0, s57
	v_lshl_add_u64 v[246:247], v[252:253], 0, s[94:95]
	global_load_lds_dwordx4 v[246:247], off
	s_barrier
	s_waitcnt lgkmcnt(7)
	v_mfma_f32_16x16x32_bf16 v[62:65], v[82:85], v[176:179], v[62:65]
	v_mfma_f32_16x16x32_bf16 v[58:61], v[90:93], v[176:179], v[58:61]
	s_waitcnt lgkmcnt(5)
	v_mfma_f32_16x16x32_bf16 v[46:49], v[82:85], v[184:187], v[46:49]
	v_mfma_f32_16x16x32_bf16 v[42:45], v[90:93], v[184:187], v[42:45]
	s_waitcnt lgkmcnt(3)
	v_mfma_f32_16x16x32_bf16 v[30:33], v[82:85], v[214:217], v[30:33]
	v_mfma_f32_16x16x32_bf16 v[26:29], v[90:93], v[214:217], v[26:29]
	s_waitcnt lgkmcnt(1)
	v_mfma_f32_16x16x32_bf16 v[14:17], v[82:85], v[222:225], v[14:17]
	v_mfma_f32_16x16x32_bf16 v[10:13], v[90:93], v[222:225], v[10:13]
	v_mfma_f32_16x16x32_bf16 v[62:65], v[86:89], v[180:183], v[62:65]
	v_mfma_f32_16x16x32_bf16 v[58:61], v[94:97], v[180:183], v[58:61]
	v_mfma_f32_16x16x32_bf16 v[46:49], v[86:89], v[210:213], v[46:49]
	v_mfma_f32_16x16x32_bf16 v[42:45], v[94:97], v[210:213], v[42:45]
	v_mfma_f32_16x16x32_bf16 v[30:33], v[86:89], v[218:221], v[30:33]
	v_mfma_f32_16x16x32_bf16 v[26:29], v[94:97], v[218:221], v[26:29]
	s_waitcnt lgkmcnt(0)
	v_mfma_f32_16x16x32_bf16 v[14:17], v[86:89], v[226:229], v[14:17]
	v_mfma_f32_16x16x32_bf16 v[10:13], v[94:97], v[226:229], v[10:13]
	s_barrier
	s_add_u32 s44, s44, 0x40080
	s_addc_u32 s45, s45, 0
	s_add_i32 s46, s46, s50
	s_mov_b32 m0, s46
	s_nop 0
	global_load_lds_dwordx4 v164, s[44:45]
	s_add_i32 m0, s46, 0x2000
	s_nop 0
	global_load_lds_dwordx4 v168, s[44:45]
	s_waitcnt vmcnt(6)
	s_barrier
	v_mfma_f32_16x16x32_bf16 v[54:57], v[230:233], v[176:179], v[54:57]
	v_mfma_f32_16x16x32_bf16 v[50:53], v[238:241], v[176:179], v[50:53]
	v_mfma_f32_16x16x32_bf16 v[38:41], v[230:233], v[184:187], v[38:41]
	v_mfma_f32_16x16x32_bf16 v[34:37], v[238:241], v[184:187], v[34:37]
	v_mfma_f32_16x16x32_bf16 v[22:25], v[230:233], v[214:217], v[22:25]
	v_mfma_f32_16x16x32_bf16 v[18:21], v[238:241], v[214:217], v[18:21]
	v_mfma_f32_16x16x32_bf16 v[6:9], v[230:233], v[222:225], v[6:9]
	v_mfma_f32_16x16x32_bf16 v[2:5], v[238:241], v[222:225], v[2:5]
	v_mfma_f32_16x16x32_bf16 v[54:57], v[234:237], v[180:183], v[54:57]
	v_mfma_f32_16x16x32_bf16 v[50:53], v[242:245], v[180:183], v[50:53]
	v_mfma_f32_16x16x32_bf16 v[38:41], v[234:237], v[210:213], v[38:41]
	v_mfma_f32_16x16x32_bf16 v[34:37], v[242:245], v[210:213], v[34:37]
	v_mfma_f32_16x16x32_bf16 v[22:25], v[234:237], v[218:221], v[22:25]
	v_mfma_f32_16x16x32_bf16 v[18:21], v[242:245], v[218:221], v[18:21]
	v_mfma_f32_16x16x32_bf16 v[6:9], v[234:237], v[226:229], v[6:9]
	v_mfma_f32_16x16x32_bf16 v[2:5], v[242:245], v[226:229], v[2:5]
	s_barrier
	s_add_i32 s62, s62, 2
	s_add_u32 s60, s60, 0x100
	s_addc_u32 s61, s61, 0
	s_add_u32 s42, s42, 0x100
	s_addc_u32 s43, s43, 0
	s_cmp_gt_u32 s62, 13
	s_cbranch_scc0 .LBB0_360
	v_lshl_or_b32 v180, s0, 8, v207
	v_ashrrev_i32_e32 v181, 31, v180
	v_mov_b32_e32 v86, 0
	v_cndmask_b32_e64 v0, 0, 1, s[26:27]
	v_lshl_add_u64 v[176:177], v[180:181], 2, s[22:23]
	v_cmp_ne_u32_e64 s[0:1], 1, v0
	s_andn2_b64 vcc, exec, s[26:27]
	v_mov_b32_e32 v94, 0
	v_mov_b32_e32 v95, v86
	v_mov_b32_e32 v96, 0
	v_mov_b32_e32 v97, 0
	s_cbranch_vccnz .LBB0_363
	global_load_dwordx4 v[94:97], v[176:177], off

.Lkprio_0:
.LBB0_586:
	s_add_u32 s22, s20, 0xfffc0080
	s_addc_u32 s23, s21, -1
	s_add_i32 s48, 0, 0x10000
	v_add_u32_e32 v140, s48, v143
	ds_read_b128 v[162:165], v140
	ds_read_b128 v[166:169], v140 offset:1024
	ds_read_b128 v[170:173], v140 offset:2048
	ds_read_b128 v[174:177], v140 offset:3072
	s_cmp_eq_u32 s47, 12
	s_cselect_b32 s25, s9, s23
	s_cselect_b32 s24, s43, s22
	s_cselect_b32 s23, s1, s46
	s_cselect_b32 s22, s44, s45
	v_lshl_add_u64 v[140:141], s[20:21], 0, v[136:137]
	s_add_i32 m0, s3, 0xc000
	ds_read_b128 v[178:181], v145
	ds_read_b128 v[182:185], v145 offset:1024
	ds_read_b128 v[206:209], v145 offset:2048
	ds_read_b128 v[210:213], v145 offset:3072
	ds_read_b128 v[214:217], v145 offset:4096
	ds_read_b128 v[218:221], v145 offset:5120
	ds_read_b128 v[222:225], v145 offset:6144
	ds_read_b128 v[226:229], v145 offset:7168
	global_load_lds_dwordx4 v[140:141], off
	s_add_i32 m0, s3, 0xe000
	s_nop 0
	global_load_lds_dwordx4 v138, s[20:21]
	s_waitcnt lgkmcnt(8)
	s_barrier
	s_waitcnt lgkmcnt(7)
	v_mfma_f32_16x16x32_bf16 v[122:125], v[162:165], v[178:181], v[122:125]
	v_mfma_f32_16x16x32_bf16 v[114:117], v[170:173], v[178:181], v[114:117]
	s_waitcnt lgkmcnt(5)
	v_mfma_f32_16x16x32_bf16 v[106:109], v[162:165], v[206:209], v[106:109]
	v_mfma_f32_16x16x32_bf16 v[98:101], v[170:173], v[206:209], v[98:101]
	s_waitcnt lgkmcnt(3)
	v_mfma_f32_16x16x32_bf16 v[90:93], v[162:165], v[214:217], v[90:93]
	v_mfma_f32_16x16x32_bf16 v[82:85], v[170:173], v[214:217], v[82:85]
	s_waitcnt lgkmcnt(1)
	v_mfma_f32_16x16x32_bf16 v[74:77], v[162:165], v[222:225], v[74:77]
	v_mfma_f32_16x16x32_bf16 v[66:69], v[170:173], v[222:225], v[66:69]
	v_mfma_f32_16x16x32_bf16 v[122:125], v[166:169], v[182:185], v[122:125]
	v_mfma_f32_16x16x32_bf16 v[114:117], v[174:177], v[182:185], v[114:117]
	v_mfma_f32_16x16x32_bf16 v[106:109], v[166:169], v[210:213], v[106:109]
	v_mfma_f32_16x16x32_bf16 v[98:101], v[174:177], v[210:213], v[98:101]
	v_mfma_f32_16x16x32_bf16 v[90:93], v[166:169], v[218:221], v[90:93]
	v_mfma_f32_16x16x32_bf16 v[82:85], v[174:177], v[218:221], v[82:85]
	s_waitcnt lgkmcnt(0)
	v_mfma_f32_16x16x32_bf16 v[74:77], v[166:169], v[226:229], v[74:77]
	v_mfma_f32_16x16x32_bf16 v[66:69], v[174:177], v[226:229], v[66:69]
	s_barrier
	s_add_i32 s50, 0, 0x14000
	v_add_u32_e32 v140, s50, v143
	s_add_i32 s48, s48, s29
	ds_read_b128 v[230:233], v140
	ds_read_b128 v[234:237], v140 offset:1024
	ds_read_b128 v[238:241], v140 offset:2048
	ds_read_b128 v[242:245], v140 offset:3072
	v_lshl_add_u64 v[140:141], s[22:23], 0, v[0:1]
	s_mov_b32 m0, s48
	v_lshl_add_u64 v[186:187], s[22:23], 0, v[130:131]
	global_load_lds_dwordx4 v[140:141], off
	s_add_i32 m0, s48, 0x2000
	s_nop 0
	global_load_lds_dwordx4 v[186:187], off
	s_barrier
	s_waitcnt lgkmcnt(3)
	v_mfma_f32_16x16x32_bf16 v[126:129], v[230:233], v[178:181], v[126:129]
	s_waitcnt lgkmcnt(1)
	v_mfma_f32_16x16x32_bf16 v[118:121], v[238:241], v[178:181], v[118:121]
	v_mfma_f32_16x16x32_bf16 v[110:113], v[230:233], v[206:209], v[110:113]
	v_mfma_f32_16x16x32_bf16 v[102:105], v[238:241], v[206:209], v[102:105]
	v_mfma_f32_16x16x32_bf16 v[94:97], v[230:233], v[214:217], v[94:97]
	v_mfma_f32_16x16x32_bf16 v[86:89], v[238:241], v[214:217], v[86:89]
	v_mfma_f32_16x16x32_bf16 v[78:81], v[230:233], v[222:225], v[78:81]
	v_mfma_f32_16x16x32_bf16 v[70:73], v[238:241], v[222:225], v[70:73]
	v_mfma_f32_16x16x32_bf16 v[126:129], v[234:237], v[182:185], v[126:129]
	s_waitcnt lgkmcnt(0)
	v_mfma_f32_16x16x32_bf16 v[118:121], v[242:245], v[182:185], v[118:121]
	v_mfma_f32_16x16x32_bf16 v[110:113], v[234:237], v[210:213], v[110:113]
	v_mfma_f32_16x16x32_bf16 v[102:105], v[242:245], v[210:213], v[102:105]
	v_mfma_f32_16x16x32_bf16 v[94:97], v[234:237], v[218:221], v[94:97]
	v_mfma_f32_16x16x32_bf16 v[86:89], v[242:245], v[218:221], v[86:89]
	v_mfma_f32_16x16x32_bf16 v[78:81], v[234:237], v[226:229], v[78:81]
	v_mfma_f32_16x16x32_bf16 v[70:73], v[242:245], v[226:229], v[70:73]
	s_barrier
	s_mov_b32 m0, s3
	v_lshl_add_u64 v[246:247], s[24:25], 0, v[134:135]
	ds_read_b128 v[178:181], v145 offset:16384
	ds_read_b128 v[182:185], v145 offset:17408
	ds_read_b128 v[206:209], v145 offset:18432
	ds_read_b128 v[210:213], v145 offset:19456
	ds_read_b128 v[214:217], v145 offset:20480
	ds_read_b128 v[218:221], v145 offset:21504
	ds_read_b128 v[222:225], v145 offset:22528
	ds_read_b128 v[226:229], v145 offset:23552
	global_load_lds_dwordx4 v[246:247], off
	s_mov_b32 m0, s31
	v_lshl_add_u64 v[248:249], s[24:25], 0, v[132:133]
	global_load_lds_dwordx4 v[248:249], off
	s_barrier
	s_waitcnt lgkmcnt(7)
	v_mfma_f32_16x16x32_bf16 v[58:61], v[162:165], v[178:181], v[58:61]
	v_mfma_f32_16x16x32_bf16 v[50:53], v[170:173], v[178:181], v[50:53]
	s_waitcnt lgkmcnt(5)
	v_mfma_f32_16x16x32_bf16 v[42:45], v[162:165], v[206:209], v[42:45]
	v_mfma_f32_16x16x32_bf16 v[34:37], v[170:173], v[206:209], v[34:37]
	s_waitcnt lgkmcnt(3)
	v_mfma_f32_16x16x32_bf16 v[26:29], v[162:165], v[214:217], v[26:29]
	v_mfma_f32_16x16x32_bf16 v[18:21], v[170:173], v[214:217], v[18:21]
	s_waitcnt lgkmcnt(1)
	v_mfma_f32_16x16x32_bf16 v[10:13], v[162:165], v[222:225], v[10:13]
	v_mfma_f32_16x16x32_bf16 v[6:9], v[170:173], v[222:225], v[6:9]
	v_mfma_f32_16x16x32_bf16 v[58:61], v[166:169], v[182:185], v[58:61]
	v_mfma_f32_16x16x32_bf16 v[50:53], v[174:177], v[182:185], v[50:53]
	v_mfma_f32_16x16x32_bf16 v[42:45], v[166:169], v[210:213], v[42:45]
	v_mfma_f32_16x16x32_bf16 v[34:37], v[174:177], v[210:213], v[34:37]
	v_mfma_f32_16x16x32_bf16 v[26:29], v[166:169], v[218:221], v[26:29]
	v_mfma_f32_16x16x32_bf16 v[18:21], v[174:177], v[218:221], v[18:21]
	s_waitcnt lgkmcnt(0)
	v_mfma_f32_16x16x32_bf16 v[10:13], v[166:169], v[226:229], v[10:13]
	v_mfma_f32_16x16x32_bf16 v[6:9], v[174:177], v[226:229], v[6:9]
	s_barrier
	s_add_u32 s48, s22, 0x40000
	s_addc_u32 s49, s23, 0
	s_add_i32 s50, s50, s29
	s_mov_b32 m0, s50
	s_nop 0
	global_load_lds_dwordx4 v0, s[48:49]
	s_add_i32 m0, s50, 0x2000
	s_nop 0
	global_load_lds_dwordx4 v130, s[48:49]
	s_waitcnt vmcnt(6)
	s_barrier
	v_mfma_f32_16x16x32_bf16 v[62:65], v[230:233], v[178:181], v[62:65]
	v_mfma_f32_16x16x32_bf16 v[54:57], v[238:241], v[178:181], v[54:57]
	v_mfma_f32_16x16x32_bf16 v[46:49], v[230:233], v[206:209], v[46:49]
	v_mfma_f32_16x16x32_bf16 v[38:41], v[238:241], v[206:209], v[38:41]
	v_mfma_f32_16x16x32_bf16 v[30:33], v[230:233], v[214:217], v[30:33]
	v_mfma_f32_16x16x32_bf16 v[22:25], v[238:241], v[214:217], v[22:25]
	v_mfma_f32_16x16x32_bf16 v[14:17], v[230:233], v[222:225], v[14:17]
	v_mfma_f32_16x16x32_bf16 v[2:5], v[238:241], v[222:225], v[2:5]
	v_mfma_f32_16x16x32_bf16 v[62:65], v[234:237], v[182:185], v[62:65]
	v_mfma_f32_16x16x32_bf16 v[54:57], v[242:245], v[182:185], v[54:57]
	v_mfma_f32_16x16x32_bf16 v[46:49], v[234:237], v[210:213], v[46:49]
	v_mfma_f32_16x16x32_bf16 v[38:41], v[242:245], v[210:213], v[38:41]
	v_mfma_f32_16x16x32_bf16 v[30:33], v[234:237], v[218:221], v[30:33]
	v_mfma_f32_16x16x32_bf16 v[22:25], v[242:245], v[218:221], v[22:25]
	v_mfma_f32_16x16x32_bf16 v[14:17], v[234:237], v[226:229], v[14:17]
	v_mfma_f32_16x16x32_bf16 v[2:5], v[242:245], v[226:229], v[2:5]
	s_barrier
	s_add_i32 s48, 0, 0x18000
	v_add_u32_e32 v174, s48, v143
	ds_read_b128 v[162:165], v174
	ds_read_b128 v[166:169], v174 offset:1024
	ds_read_b128 v[170:173], v174 offset:2048
	ds_read_b128 v[174:177], v174 offset:3072
	s_add_u32 s24, s24, 0x40000
	s_addc_u32 s25, s25, 0
	s_mov_b32 m0, s34
	v_lshl_add_u64 v[230:231], s[24:25], 0, v[134:135]
	ds_read_b128 v[178:181], v145 offset:32768
	ds_read_b128 v[182:185], v145 offset:33792
	ds_read_b128 v[206:209], v145 offset:34816
	ds_read_b128 v[210:213], v145 offset:35840
	ds_read_b128 v[214:217], v145 offset:36864
	ds_read_b128 v[218:221], v145 offset:37888
	ds_read_b128 v[222:225], v145 offset:38912
	ds_read_b128 v[226:229], v145 offset:39936
	global_load_lds_dwordx4 v[230:231], off
	s_mov_b32 m0, s35
	s_nop 0
	global_load_lds_dwordx4 v132, s[24:25]
	s_waitcnt lgkmcnt(8)
	s_barrier
	s_waitcnt lgkmcnt(7)
	v_mfma_f32_16x16x32_bf16 v[122:125], v[162:165], v[178:181], v[122:125]
	v_mfma_f32_16x16x32_bf16 v[114:117], v[170:173], v[178:181], v[114:117]
	s_waitcnt lgkmcnt(5)
	v_mfma_f32_16x16x32_bf16 v[106:109], v[162:165], v[206:209], v[106:109]
	v_mfma_f32_16x16x32_bf16 v[98:101], v[170:173], v[206:209], v[98:101]
	s_waitcnt lgkmcnt(3)
	v_mfma_f32_16x16x32_bf16 v[90:93], v[162:165], v[214:217], v[90:93]
	v_mfma_f32_16x16x32_bf16 v[82:85], v[170:173], v[214:217], v[82:85]
	s_waitcnt lgkmcnt(1)
	v_mfma_f32_16x16x32_bf16 v[74:77], v[162:165], v[222:225], v[74:77]
	v_mfma_f32_16x16x32_bf16 v[66:69], v[170:173], v[222:225], v[66:69]
	v_mfma_f32_16x16x32_bf16 v[122:125], v[166:169], v[182:185], v[122:125]
	v_mfma_f32_16x16x32_bf16 v[114:117], v[174:177], v[182:185], v[114:117]
	v_mfma_f32_16x16x32_bf16 v[106:109], v[166:169], v[210:213], v[106:109]
	v_mfma_f32_16x16x32_bf16 v[98:101], v[174:177], v[210:213], v[98:101]
	v_mfma_f32_16x16x32_bf16 v[90:93], v[166:169], v[218:221], v[90:93]
	v_mfma_f32_16x16x32_bf16 v[82:85], v[174:177], v[218:221], v[82:85]
	s_waitcnt lgkmcnt(0)
	v_mfma_f32_16x16x32_bf16 v[74:77], v[166:169], v[226:229], v[74:77]
	v_mfma_f32_16x16x32_bf16 v[66:69], v[174:177], v[226:229], v[66:69]
	s_barrier
	s_add_i32 s24, 0, 0x1c000
	s_add_i32 s25, s48, s29
	v_add_u32_e32 v205, s24, v143
	v_lshl_add_u64 v[140:141], v[140:141], 0, s[94:95]
	s_mov_b32 m0, s25
	ds_read_b128 v[230:233], v205
	ds_read_b128 v[234:237], v205 offset:1024
	ds_read_b128 v[238:241], v205 offset:2048
	ds_read_b128 v[242:245], v205 offset:3072
	global_load_lds_dwordx4 v[140:141], off
	s_add_i32 m0, s25, 0x2000
	v_lshl_add_u64 v[140:141], v[186:187], 0, s[94:95]
	global_load_lds_dwordx4 v[140:141], off
	s_barrier
	s_waitcnt lgkmcnt(3)
	v_mfma_f32_16x16x32_bf16 v[126:129], v[230:233], v[178:181], v[126:129]
	s_waitcnt lgkmcnt(1)
	v_mfma_f32_16x16x32_bf16 v[118:121], v[238:241], v[178:181], v[118:121]
	v_mfma_f32_16x16x32_bf16 v[110:113], v[230:233], v[206:209], v[110:113]
	v_mfma_f32_16x16x32_bf16 v[102:105], v[238:241], v[206:209], v[102:105]
	v_mfma_f32_16x16x32_bf16 v[94:97], v[230:233], v[214:217], v[94:97]
	v_mfma_f32_16x16x32_bf16 v[86:89], v[238:241], v[214:217], v[86:89]
	v_mfma_f32_16x16x32_bf16 v[78:81], v[230:233], v[222:225], v[78:81]
	v_mfma_f32_16x16x32_bf16 v[70:73], v[238:241], v[222:225], v[70:73]
	v_mfma_f32_16x16x32_bf16 v[126:129], v[234:237], v[182:185], v[126:129]
	s_waitcnt lgkmcnt(0)
	v_mfma_f32_16x16x32_bf16 v[118:121], v[242:245], v[182:185], v[118:121]
	v_mfma_f32_16x16x32_bf16 v[110:113], v[234:237], v[210:213], v[110:113]
	v_mfma_f32_16x16x32_bf16 v[102:105], v[242:245], v[210:213], v[102:105]
	v_mfma_f32_16x16x32_bf16 v[94:97], v[234:237], v[218:221], v[94:97]
	v_mfma_f32_16x16x32_bf16 v[86:89], v[242:245], v[218:221], v[86:89]
	v_mfma_f32_16x16x32_bf16 v[78:81], v[234:237], v[226:229], v[78:81]
	v_mfma_f32_16x16x32_bf16 v[70:73], v[242:245], v[226:229], v[70:73]
	s_barrier
	s_mov_b32 m0, s37
	v_lshl_add_u64 v[140:141], v[246:247], 0, s[94:95]
	ds_read_b128 v[178:181], v145 offset:49152
	ds_read_b128 v[182:185], v145 offset:50176
	ds_read_b128 v[206:209], v145 offset:51200
	ds_read_b128 v[210:213], v145 offset:52224
	ds_read_b128 v[214:217], v145 offset:53248
	ds_read_b128 v[218:221], v145 offset:54272
	ds_read_b128 v[222:225], v145 offset:55296
	ds_read_b128 v[226:229], v145 offset:56320
	global_load_lds_dwordx4 v[140:141], off
	s_mov_b32 m0, s40
	v_lshl_add_u64 v[140:141], v[248:249], 0, s[94:95]
	global_load_lds_dwordx4 v[140:141], off
	s_barrier
	s_waitcnt lgkmcnt(7)
	v_mfma_f32_16x16x32_bf16 v[58:61], v[162:165], v[178:181], v[58:61]
	v_mfma_f32_16x16x32_bf16 v[50:53], v[170:173], v[178:181], v[50:53]
	s_waitcnt lgkmcnt(5)
	v_mfma_f32_16x16x32_bf16 v[42:45], v[162:165], v[206:209], v[42:45]
	v_mfma_f32_16x16x32_bf16 v[34:37], v[170:173], v[206:209], v[34:37]
	s_waitcnt lgkmcnt(3)
	v_mfma_f32_16x16x32_bf16 v[26:29], v[162:165], v[214:217], v[26:29]
	v_mfma_f32_16x16x32_bf16 v[18:21], v[170:173], v[214:217], v[18:21]
	s_waitcnt lgkmcnt(1)
	v_mfma_f32_16x16x32_bf16 v[10:13], v[162:165], v[222:225], v[10:13]
	v_mfma_f32_16x16x32_bf16 v[6:9], v[170:173], v[222:225], v[6:9]
	v_mfma_f32_16x16x32_bf16 v[58:61], v[166:169], v[182:185], v[58:61]
	v_mfma_f32_16x16x32_bf16 v[50:53], v[174:177], v[182:185], v[50:53]
	v_mfma_f32_16x16x32_bf16 v[42:45], v[166:169], v[210:213], v[42:45]
	v_mfma_f32_16x16x32_bf16 v[34:37], v[174:177], v[210:213], v[34:37]
	v_mfma_f32_16x16x32_bf16 v[26:29], v[166:169], v[218:221], v[26:29]
	v_mfma_f32_16x16x32_bf16 v[18:21], v[174:177], v[218:221], v[18:21]
	s_waitcnt lgkmcnt(0)
	v_mfma_f32_16x16x32_bf16 v[10:13], v[166:169], v[226:229], v[10:13]
	v_mfma_f32_16x16x32_bf16 v[6:9], v[174:177], v[226:229], v[6:9]
	s_barrier
	s_add_u32 s22, s22, 0x40080
	s_addc_u32 s23, s23, 0
	s_add_i32 s24, s24, s29
	s_mov_b32 m0, s24
	s_nop 0
	global_load_lds_dwordx4 v0, s[22:23]
	s_add_i32 m0, s24, 0x2000
	s_nop 0
	global_load_lds_dwordx4 v130, s[22:23]
	s_waitcnt vmcnt(6)
	s_barrier
	v_mfma_f32_16x16x32_bf16 v[62:65], v[230:233], v[178:181], v[62:65]
	v_mfma_f32_16x16x32_bf16 v[54:57], v[238:241], v[178:181], v[54:57]
	v_mfma_f32_16x16x32_bf16 v[46:49], v[230:233], v[206:209], v[46:49]
	v_mfma_f32_16x16x32_bf16 v[38:41], v[238:241], v[206:209], v[38:41]
	v_mfma_f32_16x16x32_bf16 v[30:33], v[230:233], v[214:217], v[30:33]
	v_mfma_f32_16x16x32_bf16 v[22:25], v[238:241], v[214:217], v[22:25]
	v_mfma_f32_16x16x32_bf16 v[14:17], v[230:233], v[222:225], v[14:17]
	v_mfma_f32_16x16x32_bf16 v[2:5], v[238:241], v[222:225], v[2:5]
	v_mfma_f32_16x16x32_bf16 v[62:65], v[234:237], v[182:185], v[62:65]
	v_mfma_f32_16x16x32_bf16 v[54:57], v[242:245], v[182:185], v[54:57]
	v_mfma_f32_16x16x32_bf16 v[46:49], v[234:237], v[210:213], v[46:49]
	v_mfma_f32_16x16x32_bf16 v[38:41], v[242:245], v[210:213], v[38:41]
	v_mfma_f32_16x16x32_bf16 v[30:33], v[234:237], v[218:221], v[30:33]
	v_mfma_f32_16x16x32_bf16 v[22:25], v[242:245], v[218:221], v[22:25]
	v_mfma_f32_16x16x32_bf16 v[14:17], v[234:237], v[226:229], v[14:17]
	v_mfma_f32_16x16x32_bf16 v[2:5], v[242:245], v[226:229], v[2:5]
	s_barrier
	s_add_i32 s47, s47, 2
	s_add_u32 s20, s20, 0x100
	s_addc_u32 s21, s21, 0
	s_add_u32 s45, s45, 0x100
	s_addc_u32 s46, s46, 0
	s_cmp_gt_u32 s47, 13
	s_cbranch_scc0 .LBB0_586
	v_pk_mul_f32 v[164:165], v[122:123], s[4:5] op_sel_hi:[1,0]
	v_pk_mul_f32 v[122:123], v[122:123], v[126:127]
	v_pk_mul_f32 v[126:127], v[114:115], s[4:5] op_sel_hi:[1,0]
	v_pk_mul_f32 v[114:115], v[114:115], v[118:119]
	v_exp_f32_e32 v126, v126
	v_exp_f32_e32 v127, v127
	v_pk_mul_f32 v[128:129], v[124:125], v[128:129]
	v_pk_mul_f32 v[124:125], v[124:125], s[4:5] op_sel_hi:[1,0]
	v_exp_f32_e32 v164, v164
	v_pk_add_f32 v[126:127], v[126:127], 1.0 op_sel_hi:[1,0]
	v_exp_f32_e32 v165, v165
	v_rcp_f32_e32 v126, v126
	v_rcp_f32_e32 v127, v127
	v_exp_f32_e32 v124, v124
	v_exp_f32_e32 v125, v125
	v_pk_add_f32 v[164:165], v[164:165], 1.0 op_sel_hi:[1,0]
	v_pk_mul_f32 v[118:119], v[126:127], v[114:115]
	v_pk_mul_f32 v[114:115], v[116:117], s[4:5] op_sel_hi:[1,0]
	v_pk_add_f32 v[124:125], v[124:125], 1.0 op_sel_hi:[1,0]
	v_exp_f32_e32 v114, v114
	v_exp_f32_e32 v115, v115
	v_rcp_f32_e32 v164, v164
	v_rcp_f32_e32 v165, v165
	v_rcp_f32_e32 v124, v124
	v_pk_add_f32 v[114:115], v[114:115], 1.0 op_sel_hi:[1,0]
	v_rcp_f32_e32 v125, v125
	v_rcp_f32_e32 v114, v114
	v_rcp_f32_e32 v115, v115
	v_lshl_or_b32 v140, s42, 7, v144
	v_ashrrev_i32_e32 v141, 31, v140
	v_lshl_add_u32 v162, s2, 8, v142
	v_lshl_add_u64 v[140:141], v[140:141], 1, s[14:15]
	v_pk_mul_f32 v[120:121], v[116:117], v[120:121]
	v_pk_mul_f32 v[122:123], v[164:165], v[122:123]
	v_pk_mul_f32 v[124:125], v[124:125], v[128:129]
	v_pk_mul_f32 v[120:121], v[114:115], v[120:121]
	v_mad_i64_i32 v[126:127], s[20:21], v162, s91, v[140:141]
	v_cvt_pk_bf16_f32 v114, v122, v123
	v_cvt_pk_bf16_f32 v115, v124, v125
	v_cvt_pk_bf16_f32 v116, v118, v119
	v_cvt_pk_bf16_f32 v117, v120, v121
	global_store_dwordx4 v[126:127], v[114:117], off
	v_pk_mul_f32 v[112:113], v[108:109], v[112:113]
	v_pk_mul_f32 v[108:109], v[108:109], s[4:5] op_sel_hi:[1,0]
	v_pk_mul_f32 v[114:115], v[106:107], s[4:5] op_sel_hi:[1,0]
	v_pk_mul_f32 v[106:107], v[106:107], v[110:111]
	v_pk_mul_f32 v[110:111], v[98:99], s[4:5] op_sel_hi:[1,0]
	v_pk_mul_f32 v[98:99], v[98:99], v[102:103]
	v_exp_f32_e32 v110, v110
	v_exp_f32_e32 v111, v111
	v_exp_f32_e32 v114, v114
	v_exp_f32_e32 v115, v115
	v_exp_f32_e32 v108, v108
	v_pk_add_f32 v[110:111], v[110:111], 1.0 op_sel_hi:[1,0]
	v_exp_f32_e32 v109, v109
	v_rcp_f32_e32 v110, v110
	v_rcp_f32_e32 v111, v111
	v_pk_add_f32 v[114:115], v[114:115], 1.0 op_sel_hi:[1,0]
	v_pk_add_f32 v[108:109], v[108:109], 1.0 op_sel_hi:[1,0]
	v_rcp_f32_e32 v114, v114
	v_pk_mul_f32 v[102:103], v[110:111], v[98:99]
	v_pk_mul_f32 v[98:99], v[100:101], s[4:5] op_sel_hi:[1,0]
	v_rcp_f32_e32 v115, v115
	v_exp_f32_e32 v98, v98
	v_exp_f32_e32 v99, v99
	v_rcp_f32_e32 v108, v108
	v_rcp_f32_e32 v109, v109
	v_or_b32_e32 v116, 16, v162
	v_pk_add_f32 v[98:99], v[98:99], 1.0 op_sel_hi:[1,0]
	v_pk_mul_f32 v[104:105], v[100:101], v[104:105]
	v_rcp_f32_e32 v98, v98
	v_rcp_f32_e32 v99, v99
	v_pk_mul_f32 v[106:107], v[114:115], v[106:107]
	v_pk_mul_f32 v[108:109], v[108:109], v[112:113]
	v_mad_i64_i32 v[110:111], s[20:21], v116, s91, v[140:141]
	v_pk_mul_f32 v[104:105], v[98:99], v[104:105]
	v_cvt_pk_bf16_f32 v98, v106, v107
	v_cvt_pk_bf16_f32 v99, v108, v109
	v_cvt_pk_bf16_f32 v100, v102, v103
	v_pk_mul_f32 v[96:97], v[92:93], v[96:97]
	v_cvt_pk_bf16_f32 v101, v104, v105
	global_store_dwordx4 v[110:111], v[98:101], off
	v_pk_mul_f32 v[92:93], v[92:93], s[4:5] op_sel_hi:[1,0]
	v_pk_mul_f32 v[88:89], v[84:85], v[88:89]
	v_pk_mul_f32 v[98:99], v[90:91], s[4:5] op_sel_hi:[1,0]
	v_pk_mul_f32 v[90:91], v[90:91], v[94:95]
	v_pk_mul_f32 v[94:95], v[82:83], s[4:5] op_sel_hi:[1,0]
	v_pk_mul_f32 v[82:83], v[82:83], v[86:87]
	v_exp_f32_e32 v94, v94
	v_exp_f32_e32 v95, v95
	v_exp_f32_e32 v98, v98
	v_exp_f32_e32 v99, v99
	v_exp_f32_e32 v92, v92
	v_pk_add_f32 v[94:95], v[94:95], 1.0 op_sel_hi:[1,0]
	v_exp_f32_e32 v93, v93
	v_rcp_f32_e32 v94, v94
	v_rcp_f32_e32 v95, v95
	v_pk_add_f32 v[98:99], v[98:99], 1.0 op_sel_hi:[1,0]
	v_pk_add_f32 v[92:93], v[92:93], 1.0 op_sel_hi:[1,0]
	v_rcp_f32_e32 v98, v98
	v_pk_mul_f32 v[86:87], v[94:95], v[82:83]
	v_pk_mul_f32 v[82:83], v[84:85], s[4:5] op_sel_hi:[1,0]
	v_rcp_f32_e32 v99, v99
	v_exp_f32_e32 v82, v82
	v_exp_f32_e32 v83, v83
	v_rcp_f32_e32 v92, v92
	v_rcp_f32_e32 v93, v93
	v_or_b32_e32 v100, 32, v162
	v_pk_add_f32 v[82:83], v[82:83], 1.0 op_sel_hi:[1,0]
	v_pk_mul_f32 v[90:91], v[98:99], v[90:91]
	v_rcp_f32_e32 v82, v82
	v_rcp_f32_e32 v83, v83
	v_pk_mul_f32 v[92:93], v[92:93], v[96:97]
	v_mad_i64_i32 v[94:95], s[20:21], v100, s91, v[140:141]
	v_pk_mul_f32 v[88:89], v[82:83], v[88:89]
	v_cvt_pk_bf16_f32 v82, v90, v91
	v_cvt_pk_bf16_f32 v83, v92, v93
	v_cvt_pk_bf16_f32 v84, v86, v87
	v_pk_mul_f32 v[80:81], v[76:77], v[80:81]
	v_cvt_pk_bf16_f32 v85, v88, v89
	global_store_dwordx4 v[94:95], v[82:85], off
	v_pk_mul_f32 v[76:77], v[76:77], s[4:5] op_sel_hi:[1,0]
	v_pk_mul_f32 v[72:73], v[68:69], v[72:73]
	v_pk_mul_f32 v[82:83], v[74:75], s[4:5] op_sel_hi:[1,0]
	v_pk_mul_f32 v[74:75], v[74:75], v[78:79]
	v_pk_mul_f32 v[78:79], v[66:67], s[4:5] op_sel_hi:[1,0]
	v_pk_mul_f32 v[66:67], v[66:67], v[70:71]
	v_exp_f32_e32 v78, v78
	v_exp_f32_e32 v79, v79
	v_exp_f32_e32 v82, v82
	v_exp_f32_e32 v83, v83
	v_exp_f32_e32 v76, v76
	v_pk_add_f32 v[78:79], v[78:79], 1.0 op_sel_hi:[1,0]
	v_exp_f32_e32 v77, v77
	v_rcp_f32_e32 v78, v78
	v_rcp_f32_e32 v79, v79
	v_pk_add_f32 v[82:83], v[82:83], 1.0 op_sel_hi:[1,0]
	v_pk_add_f32 v[76:77], v[76:77], 1.0 op_sel_hi:[1,0]
	v_rcp_f32_e32 v82, v82
	v_pk_mul_f32 v[70:71], v[78:79], v[66:67]
	v_pk_mul_f32 v[66:67], v[68:69], s[4:5] op_sel_hi:[1,0]
	v_rcp_f32_e32 v83, v83
	v_exp_f32_e32 v66, v66
	v_exp_f32_e32 v67, v67
	v_rcp_f32_e32 v76, v76
	v_rcp_f32_e32 v77, v77
	v_or_b32_e32 v84, 48, v162
	v_pk_add_f32 v[66:67], v[66:67], 1.0 op_sel_hi:[1,0]
	v_pk_mul_f32 v[74:75], v[82:83], v[74:75]
	v_rcp_f32_e32 v66, v66
	v_rcp_f32_e32 v67, v67
	v_pk_mul_f32 v[76:77], v[76:77], v[80:81]
	v_mad_i64_i32 v[78:79], s[20:21], v84, s91, v[140:141]
	v_pk_mul_f32 v[72:73], v[66:67], v[72:73]
	v_cvt_pk_bf16_f32 v66, v74, v75
	v_cvt_pk_bf16_f32 v67, v76, v77
	v_cvt_pk_bf16_f32 v68, v70, v71
	v_pk_mul_f32 v[64:65], v[60:61], v[64:65]
	v_cvt_pk_bf16_f32 v69, v72, v73
	global_store_dwordx4 v[78:79], v[66:69], off
	v_pk_mul_f32 v[60:61], v[60:61], s[4:5] op_sel_hi:[1,0]
	v_pk_mul_f32 v[56:57], v[52:53], v[56:57]
	v_pk_mul_f32 v[66:67], v[58:59], s[4:5] op_sel_hi:[1,0]
	v_pk_mul_f32 v[58:59], v[58:59], v[62:63]
	v_pk_mul_f32 v[62:63], v[50:51], s[4:5] op_sel_hi:[1,0]
	v_pk_mul_f32 v[50:51], v[50:51], v[54:55]
	v_exp_f32_e32 v62, v62
	v_exp_f32_e32 v63, v63
	v_exp_f32_e32 v66, v66
	v_exp_f32_e32 v67, v67
	v_exp_f32_e32 v60, v60
	v_pk_add_f32 v[62:63], v[62:63], 1.0 op_sel_hi:[1,0]
	v_exp_f32_e32 v61, v61
	v_rcp_f32_e32 v62, v62
	v_rcp_f32_e32 v63, v63
	v_pk_add_f32 v[66:67], v[66:67], 1.0 op_sel_hi:[1,0]
	v_pk_add_f32 v[60:61], v[60:61], 1.0 op_sel_hi:[1,0]
	v_rcp_f32_e32 v66, v66
	v_pk_mul_f32 v[54:55], v[62:63], v[50:51]
	v_pk_mul_f32 v[50:51], v[52:53], s[4:5] op_sel_hi:[1,0]
	v_rcp_f32_e32 v67, v67
	v_exp_f32_e32 v50, v50
	v_exp_f32_e32 v51, v51
	v_rcp_f32_e32 v60, v60
	v_rcp_f32_e32 v61, v61
	v_add_u32_e32 v68, 0x80, v162
	v_pk_add_f32 v[50:51], v[50:51], 1.0 op_sel_hi:[1,0]
	v_pk_mul_f32 v[58:59], v[66:67], v[58:59]
	v_rcp_f32_e32 v50, v50
	v_rcp_f32_e32 v51, v51
	v_pk_mul_f32 v[60:61], v[60:61], v[64:65]
	v_mad_i64_i32 v[62:63], s[20:21], v68, s91, v[140:141]
	v_pk_mul_f32 v[56:57], v[50:51], v[56:57]
	v_cvt_pk_bf16_f32 v50, v58, v59
	v_cvt_pk_bf16_f32 v51, v60, v61
	v_cvt_pk_bf16_f32 v52, v54, v55
	v_pk_mul_f32 v[48:49], v[44:45], v[48:49]
	v_cvt_pk_bf16_f32 v53, v56, v57
	global_store_dwordx4 v[62:63], v[50:53], off
	v_pk_mul_f32 v[44:45], v[44:45], s[4:5] op_sel_hi:[1,0]
	v_pk_mul_f32 v[40:41], v[36:37], v[40:41]
	v_pk_mul_f32 v[50:51], v[42:43], s[4:5] op_sel_hi:[1,0]
	v_pk_mul_f32 v[42:43], v[42:43], v[46:47]
	v_pk_mul_f32 v[46:47], v[34:35], s[4:5] op_sel_hi:[1,0]
	v_pk_mul_f32 v[34:35], v[34:35], v[38:39]
	v_exp_f32_e32 v46, v46
	v_exp_f32_e32 v47, v47
	v_exp_f32_e32 v50, v50
	v_exp_f32_e32 v51, v51
	v_exp_f32_e32 v44, v44
	v_pk_add_f32 v[46:47], v[46:47], 1.0 op_sel_hi:[1,0]
	v_exp_f32_e32 v45, v45
	v_rcp_f32_e32 v46, v46
	v_rcp_f32_e32 v47, v47
	v_pk_add_f32 v[50:51], v[50:51], 1.0 op_sel_hi:[1,0]
	v_pk_add_f32 v[44:45], v[44:45], 1.0 op_sel_hi:[1,0]
	v_rcp_f32_e32 v50, v50
	v_pk_mul_f32 v[38:39], v[46:47], v[34:35]
	v_pk_mul_f32 v[34:35], v[36:37], s[4:5] op_sel_hi:[1,0]
	v_rcp_f32_e32 v51, v51
	v_exp_f32_e32 v34, v34
	v_exp_f32_e32 v35, v35
	v_rcp_f32_e32 v44, v44
	v_rcp_f32_e32 v45, v45
	v_add_u32_e32 v52, 0x90, v162
	v_pk_add_f32 v[34:35], v[34:35], 1.0 op_sel_hi:[1,0]
	v_pk_mul_f32 v[42:43], v[50:51], v[42:43]
	v_rcp_f32_e32 v34, v34
	v_rcp_f32_e32 v35, v35
	v_pk_mul_f32 v[44:45], v[44:45], v[48:49]
	v_mad_i64_i32 v[46:47], s[20:21], v52, s91, v[140:141]
	v_pk_mul_f32 v[40:41], v[34:35], v[40:41]
	v_cvt_pk_bf16_f32 v34, v42, v43
	v_cvt_pk_bf16_f32 v35, v44, v45
	v_cvt_pk_bf16_f32 v36, v38, v39
	v_pk_mul_f32 v[32:33], v[28:29], v[32:33]
	v_cvt_pk_bf16_f32 v37, v40, v41
	global_store_dwordx4 v[46:47], v[34:37], off
	v_pk_mul_f32 v[28:29], v[28:29], s[4:5] op_sel_hi:[1,0]
	v_pk_mul_f32 v[24:25], v[20:21], v[24:25]
	v_pk_mul_f32 v[34:35], v[26:27], s[4:5] op_sel_hi:[1,0]
	v_pk_mul_f32 v[26:27], v[26:27], v[30:31]
	v_pk_mul_f32 v[30:31], v[18:19], s[4:5] op_sel_hi:[1,0]
	v_pk_mul_f32 v[18:19], v[18:19], v[22:23]
	v_exp_f32_e32 v30, v30
	v_exp_f32_e32 v31, v31
	v_exp_f32_e32 v34, v34
	v_exp_f32_e32 v35, v35
	v_exp_f32_e32 v28, v28
	v_pk_add_f32 v[30:31], v[30:31], 1.0 op_sel_hi:[1,0]
	v_exp_f32_e32 v29, v29
	v_rcp_f32_e32 v30, v30
	v_rcp_f32_e32 v31, v31
	v_pk_add_f32 v[34:35], v[34:35], 1.0 op_sel_hi:[1,0]
	v_pk_add_f32 v[28:29], v[28:29], 1.0 op_sel_hi:[1,0]
	v_rcp_f32_e32 v34, v34
	v_pk_mul_f32 v[22:23], v[30:31], v[18:19]
	v_pk_mul_f32 v[18:19], v[20:21], s[4:5] op_sel_hi:[1,0]
	v_rcp_f32_e32 v35, v35
	v_exp_f32_e32 v18, v18
	v_exp_f32_e32 v19, v19
	v_rcp_f32_e32 v28, v28
	v_rcp_f32_e32 v29, v29
	v_add_u32_e32 v36, 0xa0, v162
	v_pk_add_f32 v[18:19], v[18:19], 1.0 op_sel_hi:[1,0]
	v_pk_mul_f32 v[26:27], v[34:35], v[26:27]
	v_rcp_f32_e32 v18, v18
	v_rcp_f32_e32 v19, v19
	v_pk_mul_f32 v[28:29], v[28:29], v[32:33]
	v_mad_i64_i32 v[30:31], s[20:21], v36, s91, v[140:141]
	v_pk_mul_f32 v[24:25], v[18:19], v[24:25]
	v_cvt_pk_bf16_f32 v18, v26, v27
	v_cvt_pk_bf16_f32 v19, v28, v29
	v_cvt_pk_bf16_f32 v20, v22, v23
	v_pk_mul_f32 v[2:3], v[6:7], v[2:3]
	v_cvt_pk_bf16_f32 v21, v24, v25
	global_store_dwordx4 v[30:31], v[18:21], off
	v_pk_mul_f32 v[16:17], v[12:13], v[16:17]
	v_pk_mul_f32 v[12:13], v[12:13], s[4:5] op_sel_hi:[1,0]
	v_pk_mul_f32 v[18:19], v[10:11], s[4:5] op_sel_hi:[1,0]
	v_pk_mul_f32 v[10:11], v[10:11], v[14:15]
	v_pk_mul_f32 v[14:15], v[6:7], s[4:5] op_sel_hi:[1,0]
	v_exp_f32_e32 v18, v18
	v_exp_f32_e32 v14, v14
	v_exp_f32_e32 v15, v15
	v_exp_f32_e32 v19, v19
	v_exp_f32_e32 v12, v12
	v_exp_f32_e32 v13, v13
	v_pk_add_f32 v[14:15], v[14:15], 1.0 op_sel_hi:[1,0]
	v_pk_add_f32 v[18:19], v[18:19], 1.0 op_sel_hi:[1,0]
	v_rcp_f32_e32 v14, v14
	v_rcp_f32_e32 v15, v15
	v_pk_add_f32 v[12:13], v[12:13], 1.0 op_sel_hi:[1,0]
	v_rcp_f32_e32 v18, v18
	v_rcp_f32_e32 v19, v19
	v_pk_mul_f32 v[6:7], v[14:15], v[2:3]
	v_pk_mul_f32 v[2:3], v[8:9], s[4:5] op_sel_hi:[1,0]
	v_rcp_f32_e32 v12, v12
	v_exp_f32_e32 v2, v2
	v_exp_f32_e32 v3, v3
	v_rcp_f32_e32 v13, v13
	v_add_u32_e32 v20, 0xb0, v162
	v_mad_i64_i32 v[14:15], s[20:21], v20, s91, v[140:141]
	v_pk_add_f32 v[2:3], v[2:3], 1.0 op_sel_hi:[1,0]
	v_pk_mul_f32 v[4:5], v[8:9], v[4:5]
	v_rcp_f32_e32 v2, v2
	v_rcp_f32_e32 v3, v3
	s_and_b64 vcc, exec, s[38:39]
	s_mov_b32 s42, s0
	s_mov_b32 s2, s8
	s_mov_b64 s[22:23], s[18:19]
	s_mov_b64 s[20:21], s[16:17]
	v_pk_mul_f32 v[10:11], v[18:19], v[10:11]
	v_pk_mul_f32 v[12:13], v[12:13], v[16:17]
	v_pk_mul_f32 v[8:9], v[2:3], v[4:5]
	v_cvt_pk_bf16_f32 v2, v10, v11
	v_cvt_pk_bf16_f32 v3, v12, v13
	v_cvt_pk_bf16_f32 v4, v6, v7
	s_nop 0
	v_cvt_pk_bf16_f32 v5, v8, v9
	global_store_dwordx4 v[14:15], v[2:5], off
	s_cbranch_vccz .LBB0_579
	s_waitcnt vmcnt(0)
	s_cmpk_gt_u32 s26, 0xff
	s_cbranch_scc1 .LBB0_590
	s_barrier
